# out-projection GEMM epilogue rewritten: the 64 residual loads of a tile are issued together, then add+store (was a load-wait-store chain per element); nt hints on the PEER out read-modify-write; guard
# speedup vs baseline: 1.2120x; 1.0335x over previous
; #define MFMA16(a, b, c) __builtin_amdgcn_mfma_f32_16x16x32_bf16((a), (b), (c), 0, 0, 0)
; DI void gemm_mainloop(const u16* __restrict__ A, const u16* __restrict__ Bt, int tm, int tn, char* smem, f32x4 (&acc)[4][4]) {
;   const int tid = threadIdx.x, lane = tid & 63, wave = tid >> 6;
;   const int wm = wave >> 1, wn = wave & 1, g = lane >> 4, l15 = lane & 15;
;   char* As = smem; char* Bs = smem + 32768;
; #pragma unroll
;   for (int i = 0; i < 4; i++)
; #pragma unroll
;     for (int j = 0; j < 4; j++) acc[i][j] = (f32x4){0.f, 0.f, 0.f, 0.f};
;   const int lrow = tid >> 3, lch = tid & 7;
;   const u16* Ag = A + (size_t)(tm * 128 + lrow) * 1024 + lch * 8;
;   const u16* Bg = Bt + (size_t)(tn * 128 + lrow) * 1024 + lch * 8;
;   u32x4 ra[3][4], rb[3][4];
; #pragma unroll
;   for (int st = 0; st < 3; st++)
; #pragma unroll
;     for (int i = 0; i < 4; i++) {
;       ra[st][i] = *(const u32x4*)(Ag + (size_t)(32 * i) * 1024 + st * 64);
;       rb[st][i] = *(const u32x4*)(Bg + (size_t)(32 * i) * 1024 + st * 64);
;     }
;   __syncthreads();
; #pragma unroll
;   for (int i = 0; i < 4; i++) {
;     *(u32x4*)(As + gswz(lrow + 32 * i, lch)) = ra[0][i];
;     *(u32x4*)(Bs + gswz(lrow + 32 * i, lch)) = rb[0][i];
;   }
;   __syncthreads();
; #pragma unroll
;   for (int kt = 0; kt < 16; kt++) {
;     const int cur = kt & 1;
;     if (kt + 3 < 16) {
; #pragma unroll
;       for (int i = 0; i < 4; i++) {
;         ra[kt % 3][i] = *(const u32x4*)(Ag + (size_t)(32 * i) * 1024 + (kt + 3) * 64);
;         rb[kt % 3][i] = *(const u32x4*)(Bg + (size_t)(32 * i) * 1024 + (kt + 3) * 64);
;       }
;     }
;     __builtin_amdgcn_sched_barrier(0);
;     const char* Ac = As + cur * 16384; const char* Bc = Bs + cur * 16384;
; #pragma unroll
;     for (int ks = 0; ks < 2; ks++) {
;       bf16x8 af[4], bfr[4];
; #pragma unroll
;       for (int mt = 0; mt < 4; mt++) af[mt] = ldfrag(Ac, gswz(wm * 64 + mt * 16 + l15, ks * 4 + g));
; #pragma unroll
;       for (int nt = 0; nt < 4; nt++) bfr[nt] = ldfrag(Bc, gswz(wn * 64 + nt * 16 + l15, ks * 4 + g));
; #pragma unroll
;       for (int mt = 0; mt < 4; mt++)
; #pragma unroll
;         for (int nt = 0; nt < 4; nt++) acc[mt][nt] = MFMA16(af[mt], bfr[nt], acc[mt][nt]);
; DI void phase_gemm_out(const Params& p, int bid, int nb, char* smem) {
;     ...
;         }
;       }
;   }
; }
.LBB0_1043:
	s_add_i32 s9, s9, s3
	s_ashr_i32 s10, s9, 31
	s_lshr_b32 s10, s10, 26
	s_add_i32 s10, s9, s10
	s_and_b32 s11, s10, 0xffffffc0
	s_sub_i32 s11, s9, s11
	s_lshl_b32 s9, s10, 4
	s_lshl_b32 s10, s11, 7
	s_and_b32 s9, s9, 0xfffffc00
	s_and_b32 s10, s10, 0x380
	s_or_b32 s9, s10, s9
	v_or_b32_e32 v2, s9, v1
	s_lshl_b32 s10, s11, 4
	v_ashrrev_i32_e32 v3, 31, v2
	s_and_b32 s10, s10, 0xffffff80
	v_lshlrev_b64 v[2:3], 11, v[2:3]
	v_or_b32_e32 v4, s10, v1
	v_lshl_add_u64 v[2:3], v[36:37], 0, v[2:3]
	v_ashrrev_i32_e32 v5, 31, v4
	v_lshlrev_b64 v[4:5], 11, v[4:5]
	v_add_co_u32_e32 v6, vcc, s5, v2
	v_lshl_add_u64 v[4:5], v[38:39], 0, v[4:5]
	s_nop 0
	v_addc_co_u32_e32 v7, vcc, 0, v3, vcc
	v_add_co_u32_e32 v8, vcc, s5, v4
	global_load_dwordx4 v[18:21], v[2:3], off
	global_load_dwordx4 v[22:25], v[4:5], off
	v_addc_co_u32_e32 v9, vcc, 0, v5, vcc
	v_add_co_u32_e32 v10, vcc, s6, v2
	global_load_dwordx4 v[30:33], v[8:9], off
	s_nop 0
	v_addc_co_u32_e32 v11, vcc, 0, v3, vcc
	v_add_co_u32_e32 v12, vcc, s6, v4
	global_load_dwordx4 v[26:29], v[6:7], off
	s_nop 0
	v_addc_co_u32_e32 v13, vcc, 0, v5, vcc
	v_add_co_u32_e32 v14, vcc, s7, v4
	global_load_dwordx4 v[50:53], v[12:13], off
	s_nop 0
	v_addc_co_u32_e32 v15, vcc, 0, v5, vcc
	global_load_dwordx4 v[54:57], v[14:15], off
	global_load_dwordx4 v[40:43], v[10:11], off
	v_add_co_u32_e32 v16, vcc, s7, v2
	s_nop 1
	v_addc_co_u32_e32 v17, vcc, 0, v3, vcc
	global_load_dwordx4 v[58:61], v[16:17], off
	global_load_dwordx4 v[62:65], v[4:5], off offset:128
	global_load_dwordx4 v[66:69], v[4:5], off offset:256
	global_load_dwordx4 v[70:73], v[2:3], off offset:128
	global_load_dwordx4 v[74:77], v[8:9], off offset:128
	global_load_dwordx4 v[78:81], v[12:13], off offset:128
	global_load_dwordx4 v[82:85], v[14:15], off offset:128
	global_load_dwordx4 v[86:89], v[2:3], off offset:256
	global_load_dwordx4 v[90:93], v[8:9], off offset:256
	global_load_dwordx4 v[94:97], v[12:13], off offset:256
	global_load_dwordx4 v[98:101], v[14:15], off offset:256
	global_load_dwordx4 v[102:105], v[6:7], off offset:128
	global_load_dwordx4 v[106:109], v[10:11], off offset:128
	global_load_dwordx4 v[110:113], v[16:17], off offset:128
	global_load_dwordx4 v[114:117], v[6:7], off offset:256
	global_load_dwordx4 v[118:121], v[10:11], off offset:256
	global_load_dwordx4 v[122:125], v[16:17], off offset:256
	s_waitcnt vmcnt(63) expcnt(7) lgkmcnt(15)
	s_barrier
	s_waitcnt vmcnt(22)
	ds_write_b128 v35, v[22:25] offset:33024
	ds_write_b128 v35, v[18:21] offset:256
	s_waitcnt vmcnt(21)
	ds_write_b128 v35, v[30:33] offset:37120
	s_waitcnt vmcnt(19)
	ds_write_b128 v35, v[50:53] offset:41216
	s_waitcnt vmcnt(18)
	ds_write_b128 v35, v[54:57] offset:45312
	ds_write_b128 v35, v[26:29] offset:4352
	s_waitcnt vmcnt(17)
	ds_write_b128 v35, v[40:43] offset:8448
	s_waitcnt vmcnt(16)
	ds_write_b128 v35, v[58:61] offset:12544
	s_waitcnt lgkmcnt(0)
	s_barrier
	global_load_dwordx4 v[18:21], v[2:3], off offset:384
	global_load_dwordx4 v[22:25], v[4:5], off offset:384
	global_load_dwordx4 v[26:29], v[6:7], off offset:384
	global_load_dwordx4 v[30:33], v[8:9], off offset:384
	global_load_dwordx4 v[40:43], v[10:11], off offset:384
	global_load_dwordx4 v[50:53], v[12:13], off offset:384
	global_load_dwordx4 v[54:57], v[16:17], off offset:384
	global_load_dwordx4 v[58:61], v[14:15], off offset:384
	ds_read_b128 v[126:129], v45 offset:256
	ds_read_b128 v[130:133], v46 offset:33024
	ds_read_b128 v[134:137], v45 offset:2304
	ds_read_b128 v[138:141], v46 offset:35072
	ds_read_b128 v[150:153], v46 offset:37120
	ds_read_b128 v[154:157], v46 offset:39168
	ds_read_b128 v[174:177], v45 offset:4352
	ds_read_b128 v[178:181], v45 offset:6400
	s_waitcnt lgkmcnt(6)
	v_mfma_f32_16x16x32_bf16 v[142:145], v[126:129], v[130:133], 0
	s_waitcnt vmcnt(21)
	ds_write_b128 v35, v[70:73] offset:16640
	s_waitcnt vmcnt(13)
	ds_write_b128 v35, v[102:105] offset:20736
	s_waitcnt vmcnt(12)
	ds_write_b128 v35, v[106:109] offset:24832
	s_waitcnt vmcnt(11)
	ds_write_b128 v35, v[110:113] offset:28928
	s_waitcnt lgkmcnt(8)
	v_mfma_f32_16x16x32_bf16 v[146:149], v[126:129], v[138:141], 0
	s_waitcnt lgkmcnt(7)
	v_mfma_f32_16x16x32_bf16 v[158:161], v[126:129], v[150:153], 0
	s_waitcnt lgkmcnt(6)
	v_mfma_f32_16x16x32_bf16 v[126:129], v[126:129], v[154:157], 0
	v_mfma_f32_16x16x32_bf16 v[162:165], v[134:137], v[130:133], 0
	v_mfma_f32_16x16x32_bf16 v[166:169], v[134:137], v[138:141], 0
	v_mfma_f32_16x16x32_bf16 v[170:173], v[134:137], v[150:153], 0
	v_mfma_f32_16x16x32_bf16 v[134:137], v[134:137], v[154:157], 0
	s_waitcnt lgkmcnt(5)
	v_mfma_f32_16x16x32_bf16 v[182:185], v[174:177], v[130:133], 0
	v_mfma_f32_16x16x32_bf16 v[186:189], v[174:177], v[138:141], 0
	v_mfma_f32_16x16x32_bf16 v[190:193], v[174:177], v[150:153], 0
	v_mfma_f32_16x16x32_bf16 v[174:177], v[174:177], v[154:157], 0
	s_waitcnt lgkmcnt(4)
	v_mfma_f32_16x16x32_bf16 v[130:133], v[178:181], v[130:133], 0
	v_mfma_f32_16x16x32_bf16 v[138:141], v[178:181], v[138:141], 0
	v_mfma_f32_16x16x32_bf16 v[150:153], v[178:181], v[150:153], 0
	v_mfma_f32_16x16x32_bf16 v[70:73], v[178:181], v[154:157], 0
	ds_read_b128 v[102:105], v47 offset:256
	ds_read_b128 v[106:109], v48 offset:33024
	ds_read_b128 v[110:113], v47 offset:2304
	ds_read_b128 v[154:157], v48 offset:35072
	ds_read_b128 v[178:181], v48 offset:37120
	ds_read_b128 v[194:197], v48 offset:39168
	s_waitcnt lgkmcnt(4)
	v_mfma_f32_16x16x32_bf16 v[142:145], v[102:105], v[106:109], v[142:145]
	s_waitcnt lgkmcnt(2)
	v_mfma_f32_16x16x32_bf16 v[146:149], v[102:105], v[154:157], v[146:149]
	s_waitcnt lgkmcnt(1)
	v_mfma_f32_16x16x32_bf16 v[158:161], v[102:105], v[178:181], v[158:161]
	s_waitcnt lgkmcnt(0)
	v_mfma_f32_16x16x32_bf16 v[102:105], v[102:105], v[194:197], v[126:129]
	v_mfma_f32_16x16x32_bf16 v[126:129], v[110:113], v[106:109], v[162:165]
	v_mfma_f32_16x16x32_bf16 v[162:165], v[110:113], v[154:157], v[166:169]
	v_mfma_f32_16x16x32_bf16 v[166:169], v[110:113], v[178:181], v[170:173]
	v_mfma_f32_16x16x32_bf16 v[110:113], v[110:113], v[194:197], v[134:137]
	s_nop 2
	ds_read_b128 v[134:137], v47 offset:4352
	ds_read_b128 v[170:173], v47 offset:6400
	ds_write_b128 v35, v[62:65] offset:49408
	ds_write_b128 v35, v[74:77] offset:53504
	ds_write_b128 v35, v[78:81] offset:57600
	ds_write_b128 v35, v[82:85] offset:61696
	s_waitcnt lgkmcnt(5)
	v_mfma_f32_16x16x32_bf16 v[182:185], v[134:137], v[106:109], v[182:185]
	v_mfma_f32_16x16x32_bf16 v[186:189], v[134:137], v[154:157], v[186:189]
	v_mfma_f32_16x16x32_bf16 v[190:193], v[134:137], v[178:181], v[190:193]
	v_mfma_f32_16x16x32_bf16 v[134:137], v[134:137], v[194:197], v[174:177]
	s_waitcnt lgkmcnt(4)
	v_mfma_f32_16x16x32_bf16 v[106:109], v[170:173], v[106:109], v[130:133]
	v_mfma_f32_16x16x32_bf16 v[130:133], v[170:173], v[154:157], v[138:141]
	v_mfma_f32_16x16x32_bf16 v[138:141], v[170:173], v[178:181], v[150:153]
	v_mfma_f32_16x16x32_bf16 v[62:65], v[170:173], v[194:197], v[70:73]
	s_waitcnt lgkmcnt(0)
	s_barrier
; #define MFMA16(a, b, c) __builtin_amdgcn_mfma_f32_16x16x32_bf16((a), (b), (c), 0, 0, 0)
; DI void gemm_mainloop(const u16* __restrict__ A, const u16* __restrict__ Bt, int tm, int tn, char* smem, f32x4 (&acc)[4][4]) {
;     ...
; #pragma unroll
;   for (int kt = 0; kt < 16; kt++) {
;     const int cur = kt & 1;
;     if (kt + 3 < 16) {
; #pragma unroll
;       for (int i = 0; i < 4; i++) {
;         ra[kt % 3][i] = *(const u32x4*)(Ag + (size_t)(32 * i) * 1024 + (kt + 3) * 64);
;         rb[kt % 3][i] = *(const u32x4*)(Bg + (size_t)(32 * i) * 1024 + (kt + 3) * 64);
;       }
;     }
;     __builtin_amdgcn_sched_barrier(0);
;     const char* Ac = As + cur * 16384; const char* Bc = Bs + cur * 16384;
; #pragma unroll
;     for (int ks = 0; ks < 2; ks++) {
;       bf16x8 af[4], bfr[4];
; #pragma unroll
;       for (int mt = 0; mt < 4; mt++) af[mt] = ldfrag(Ac, gswz(wm * 64 + mt * 16 + l15, ks * 4 + g));
; #pragma unroll
;       for (int nt = 0; nt < 4; nt++) bfr[nt] = ldfrag(Bc, gswz(wn * 64 + nt * 16 + l15, ks * 4 + g));
; #pragma unroll
;       for (int mt = 0; mt < 4; mt++)
; #pragma unroll
;         for (int nt = 0; nt < 4; nt++) acc[mt][nt] = MFMA16(af[mt], bfr[nt], acc[mt][nt]);
;       if (kt + 1 < 16) {
;         char* Xn = (ks == 0 ? As : Bs) + (cur ^ 1) * 16384;
; #pragma unroll
;         for (int i = 0; i < 4; i++) *(u32x4*)(Xn + gswz(lrow + 32 * i, lch)) = (ks == 0 ? ra[(kt + 1) % 3][i] : rb[(kt + 1) % 3][i]);
;       }
;       __builtin_amdgcn_sched_barrier(0);
;     }
;     __syncthreads();
;   }
	s_nop 0
	global_load_dwordx4 v[70:73], v[2:3], off offset:512
	global_load_dwordx4 v[74:77], v[4:5], off offset:512
	global_load_dwordx4 v[78:81], v[6:7], off offset:512
	global_load_dwordx4 v[82:85], v[8:9], off offset:512
	global_load_dwordx4 v[150:153], v[10:11], off offset:512
	global_load_dwordx4 v[154:157], v[12:13], off offset:512
	global_load_dwordx4 v[170:173], v[16:17], off offset:512
	global_load_dwordx4 v[174:177], v[14:15], off offset:512
	ds_read_b128 v[178:181], v45 offset:16640
	ds_read_b128 v[194:197], v46 offset:49408
	ds_read_b128 v[198:201], v45 offset:18688
	ds_read_b128 v[202:205], v46 offset:51456
	ds_read_b128 v[206:209], v46 offset:53504
	ds_read_b128 v[210:213], v46 offset:55552
	s_waitcnt lgkmcnt(4)
	v_mfma_f32_16x16x32_bf16 v[142:145], v[178:181], v[194:197], v[142:145]
	s_waitcnt lgkmcnt(2)
	v_mfma_f32_16x16x32_bf16 v[146:149], v[178:181], v[202:205], v[146:149]
	s_waitcnt lgkmcnt(1)
	v_mfma_f32_16x16x32_bf16 v[158:161], v[178:181], v[206:209], v[158:161]
	s_waitcnt lgkmcnt(0)
	v_mfma_f32_16x16x32_bf16 v[102:105], v[178:181], v[210:213], v[102:105]
	v_mfma_f32_16x16x32_bf16 v[126:129], v[198:201], v[194:197], v[126:129]
	v_mfma_f32_16x16x32_bf16 v[162:165], v[198:201], v[202:205], v[162:165]
	v_mfma_f32_16x16x32_bf16 v[166:169], v[198:201], v[206:209], v[166:169]
	v_mfma_f32_16x16x32_bf16 v[110:113], v[198:201], v[210:213], v[110:113]
	ds_read_b128 v[178:181], v45 offset:20736
	ds_read_b128 v[198:201], v45 offset:22784
	ds_write_b128 v35, v[86:89] offset:256
	s_waitcnt vmcnt(18)
	ds_write_b128 v35, v[114:117] offset:4352
	s_waitcnt vmcnt(17)
	ds_write_b128 v35, v[118:121] offset:8448
	s_waitcnt vmcnt(16)
	ds_write_b128 v35, v[122:125] offset:12544
	s_waitcnt lgkmcnt(5)
	v_mfma_f32_16x16x32_bf16 v[182:185], v[178:181], v[194:197], v[182:185]
	v_mfma_f32_16x16x32_bf16 v[186:189], v[178:181], v[202:205], v[186:189]
	v_mfma_f32_16x16x32_bf16 v[190:193], v[178:181], v[206:209], v[190:193]
	v_mfma_f32_16x16x32_bf16 v[134:137], v[178:181], v[210:213], v[134:137]
	s_waitcnt lgkmcnt(4)
	v_mfma_f32_16x16x32_bf16 v[106:109], v[198:201], v[194:197], v[106:109]
	v_mfma_f32_16x16x32_bf16 v[130:133], v[198:201], v[202:205], v[130:133]
	v_mfma_f32_16x16x32_bf16 v[138:141], v[198:201], v[206:209], v[138:141]
	v_mfma_f32_16x16x32_bf16 v[62:65], v[198:201], v[210:213], v[62:65]
	ds_read_b128 v[86:89], v47 offset:16640
	ds_read_b128 v[114:117], v48 offset:49408
	ds_read_b128 v[118:121], v47 offset:18688
	ds_read_b128 v[122:125], v48 offset:51456
	ds_read_b128 v[178:181], v48 offset:53504
	ds_read_b128 v[194:197], v48 offset:55552
	s_waitcnt lgkmcnt(4)
	v_mfma_f32_16x16x32_bf16 v[142:145], v[86:89], v[114:117], v[142:145]
	s_waitcnt lgkmcnt(2)
	v_mfma_f32_16x16x32_bf16 v[146:149], v[86:89], v[122:125], v[146:149]
	s_waitcnt lgkmcnt(1)
	v_mfma_f32_16x16x32_bf16 v[158:161], v[86:89], v[178:181], v[158:161]
	s_waitcnt lgkmcnt(0)
	v_mfma_f32_16x16x32_bf16 v[86:89], v[86:89], v[194:197], v[102:105]
	v_mfma_f32_16x16x32_bf16 v[102:105], v[118:121], v[114:117], v[126:129]
	v_mfma_f32_16x16x32_bf16 v[126:129], v[118:121], v[122:125], v[162:165]
	v_mfma_f32_16x16x32_bf16 v[162:165], v[118:121], v[178:181], v[166:169]
	v_mfma_f32_16x16x32_bf16 v[110:113], v[118:121], v[194:197], v[110:113]
	ds_read_b128 v[118:121], v47 offset:20736
	s_nop 0
	ds_read_b128 v[166:169], v47 offset:22784
	ds_write_b128 v35, v[66:69] offset:33024
	ds_write_b128 v35, v[90:93] offset:37120
	ds_write_b128 v35, v[94:97] offset:41216
	ds_write_b128 v35, v[98:101] offset:45312
	s_waitcnt lgkmcnt(5)
	v_mfma_f32_16x16x32_bf16 v[182:185], v[118:121], v[114:117], v[182:185]
	v_mfma_f32_16x16x32_bf16 v[186:189], v[118:121], v[122:125], v[186:189]
	v_mfma_f32_16x16x32_bf16 v[190:193], v[118:121], v[178:181], v[190:193]
	v_mfma_f32_16x16x32_bf16 v[118:121], v[118:121], v[194:197], v[134:137]
	s_waitcnt lgkmcnt(4)
	v_mfma_f32_16x16x32_bf16 v[106:109], v[166:169], v[114:117], v[106:109]
	v_mfma_f32_16x16x32_bf16 v[114:117], v[166:169], v[122:125], v[130:133]
	v_mfma_f32_16x16x32_bf16 v[122:125], v[166:169], v[178:181], v[138:141]
	v_mfma_f32_16x16x32_bf16 v[62:65], v[166:169], v[194:197], v[62:65]
	s_waitcnt lgkmcnt(0)
	s_barrier
	global_load_dwordx4 v[66:69], v[2:3], off offset:640
	global_load_dwordx4 v[90:93], v[4:5], off offset:640
	global_load_dwordx4 v[94:97], v[6:7], off offset:640
	global_load_dwordx4 v[98:101], v[8:9], off offset:640
	global_load_dwordx4 v[130:133], v[10:11], off offset:640
	global_load_dwordx4 v[134:137], v[12:13], off offset:640
	global_load_dwordx4 v[138:141], v[16:17], off offset:640
	global_load_dwordx4 v[166:169], v[14:15], off offset:640
	ds_read_b128 v[178:181], v45 offset:256
	ds_read_b128 v[194:197], v46 offset:33024
	ds_read_b128 v[198:201], v45 offset:2304
	ds_read_b128 v[202:205], v46 offset:35072
	ds_read_b128 v[206:209], v46 offset:37120
	ds_read_b128 v[210:213], v46 offset:39168
	s_waitcnt lgkmcnt(4)
	v_mfma_f32_16x16x32_bf16 v[142:145], v[178:181], v[194:197], v[142:145]
	s_waitcnt lgkmcnt(2)
	v_mfma_f32_16x16x32_bf16 v[146:149], v[178:181], v[202:205], v[146:149]
	s_waitcnt lgkmcnt(1)
	v_mfma_f32_16x16x32_bf16 v[158:161], v[178:181], v[206:209], v[158:161]
	s_waitcnt lgkmcnt(0)
	v_mfma_f32_16x16x32_bf16 v[86:89], v[178:181], v[210:213], v[86:89]
	v_mfma_f32_16x16x32_bf16 v[102:105], v[198:201], v[194:197], v[102:105]
	v_mfma_f32_16x16x32_bf16 v[126:129], v[198:201], v[202:205], v[126:129]
	v_mfma_f32_16x16x32_bf16 v[162:165], v[198:201], v[206:209], v[162:165]
	v_mfma_f32_16x16x32_bf16 v[110:113], v[198:201], v[210:213], v[110:113]
	ds_read_b128 v[178:181], v45 offset:4352
	ds_read_b128 v[198:201], v45 offset:6400
	s_waitcnt vmcnt(23)
; #define MFMA16(a, b, c) __builtin_amdgcn_mfma_f32_16x16x32_bf16((a), (b), (c), 0, 0, 0)
; DI void gemm_mainloop(const u16* __restrict__ A, const u16* __restrict__ Bt, int tm, int tn, char* smem, f32x4 (&acc)[4][4]) {
;     ...
; #pragma unroll
;   for (int kt = 0; kt < 16; kt++) {
;     const int cur = kt & 1;
;     if (kt + 3 < 16) {
; #pragma unroll
;       for (int i = 0; i < 4; i++) {
;         ra[kt % 3][i] = *(const u32x4*)(Ag + (size_t)(32 * i) * 1024 + (kt + 3) * 64);
;         rb[kt % 3][i] = *(const u32x4*)(Bg + (size_t)(32 * i) * 1024 + (kt + 3) * 64);
;       }
;     }
;     __builtin_amdgcn_sched_barrier(0);
;     const char* Ac = As + cur * 16384; const char* Bc = Bs + cur * 16384;
; #pragma unroll
;     for (int ks = 0; ks < 2; ks++) {
;       bf16x8 af[4], bfr[4];
; #pragma unroll
;       for (int mt = 0; mt < 4; mt++) af[mt] = ldfrag(Ac, gswz(wm * 64 + mt * 16 + l15, ks * 4 + g));
; #pragma unroll
;       for (int nt = 0; nt < 4; nt++) bfr[nt] = ldfrag(Bc, gswz(wn * 64 + nt * 16 + l15, ks * 4 + g));
; #pragma unroll
;       for (int mt = 0; mt < 4; mt++)
; #pragma unroll
;         for (int nt = 0; nt < 4; nt++) acc[mt][nt] = MFMA16(af[mt], bfr[nt], acc[mt][nt]);
;       if (kt + 1 < 16) {
;         char* Xn = (ks == 0 ? As : Bs) + (cur ^ 1) * 16384;
; #pragma unroll
;         for (int i = 0; i < 4; i++) *(u32x4*)(Xn + gswz(lrow + 32 * i, lch)) = (ks == 0 ? ra[(kt + 1) % 3][i] : rb[(kt + 1) % 3][i]);
;       }
;       __builtin_amdgcn_sched_barrier(0);
;     }
;     __syncthreads();
;   }
	ds_write_b128 v35, v[18:21] offset:16640
	s_waitcnt vmcnt(21)
	ds_write_b128 v35, v[26:29] offset:20736
	s_waitcnt vmcnt(19)
	ds_write_b128 v35, v[40:43] offset:24832
	s_waitcnt vmcnt(17)
	ds_write_b128 v35, v[54:57] offset:28928
	s_waitcnt lgkmcnt(5)
	v_mfma_f32_16x16x32_bf16 v[182:185], v[178:181], v[194:197], v[182:185]
	v_mfma_f32_16x16x32_bf16 v[186:189], v[178:181], v[202:205], v[186:189]
	v_mfma_f32_16x16x32_bf16 v[190:193], v[178:181], v[206:209], v[190:193]
	v_mfma_f32_16x16x32_bf16 v[118:121], v[178:181], v[210:213], v[118:121]
	s_waitcnt lgkmcnt(4)
	v_mfma_f32_16x16x32_bf16 v[106:109], v[198:201], v[194:197], v[106:109]
	v_mfma_f32_16x16x32_bf16 v[114:117], v[198:201], v[202:205], v[114:117]
	v_mfma_f32_16x16x32_bf16 v[122:125], v[198:201], v[206:209], v[122:125]
	v_mfma_f32_16x16x32_bf16 v[18:21], v[198:201], v[210:213], v[62:65]
	ds_read_b128 v[26:29], v47 offset:256
	ds_read_b128 v[40:43], v48 offset:33024
	ds_read_b128 v[54:57], v47 offset:2304
	ds_read_b128 v[62:65], v48 offset:35072
	ds_read_b128 v[178:181], v48 offset:37120
	ds_read_b128 v[194:197], v48 offset:39168
	s_waitcnt lgkmcnt(4)
	v_mfma_f32_16x16x32_bf16 v[142:145], v[26:29], v[40:43], v[142:145]
	s_waitcnt lgkmcnt(2)
	v_mfma_f32_16x16x32_bf16 v[146:149], v[26:29], v[62:65], v[146:149]
	s_waitcnt lgkmcnt(1)
	v_mfma_f32_16x16x32_bf16 v[158:161], v[26:29], v[178:181], v[158:161]
	s_waitcnt lgkmcnt(0)
	v_mfma_f32_16x16x32_bf16 v[26:29], v[26:29], v[194:197], v[86:89]
	v_mfma_f32_16x16x32_bf16 v[86:89], v[54:57], v[40:43], v[102:105]
	v_mfma_f32_16x16x32_bf16 v[102:105], v[54:57], v[62:65], v[126:129]
	v_mfma_f32_16x16x32_bf16 v[126:129], v[54:57], v[178:181], v[162:165]
	v_mfma_f32_16x16x32_bf16 v[54:57], v[54:57], v[194:197], v[110:113]
	s_nop 2
	ds_read_b128 v[110:113], v47 offset:4352
	ds_read_b128 v[162:165], v47 offset:6400
	ds_write_b128 v35, v[22:25] offset:49408
	ds_write_b128 v35, v[30:33] offset:53504
	ds_write_b128 v35, v[50:53] offset:57600
	s_waitcnt vmcnt(16)
	ds_write_b128 v35, v[58:61] offset:61696
	s_waitcnt lgkmcnt(5)
	v_mfma_f32_16x16x32_bf16 v[182:185], v[110:113], v[40:43], v[182:185]
	v_mfma_f32_16x16x32_bf16 v[186:189], v[110:113], v[62:65], v[186:189]
	v_mfma_f32_16x16x32_bf16 v[190:193], v[110:113], v[178:181], v[190:193]
	v_mfma_f32_16x16x32_bf16 v[110:113], v[110:113], v[194:197], v[118:121]
	s_waitcnt lgkmcnt(4)
	v_mfma_f32_16x16x32_bf16 v[40:43], v[162:165], v[40:43], v[106:109]
	v_mfma_f32_16x16x32_bf16 v[62:65], v[162:165], v[62:65], v[114:117]
	v_mfma_f32_16x16x32_bf16 v[106:109], v[162:165], v[178:181], v[122:125]
	v_mfma_f32_16x16x32_bf16 v[18:21], v[162:165], v[194:197], v[18:21]
	s_waitcnt lgkmcnt(0)
	s_barrier
	global_load_dwordx4 v[22:25], v[2:3], off offset:768
	global_load_dwordx4 v[30:33], v[4:5], off offset:768
	global_load_dwordx4 v[50:53], v[6:7], off offset:768
	global_load_dwordx4 v[58:61], v[8:9], off offset:768
	global_load_dwordx4 v[114:117], v[10:11], off offset:768
	global_load_dwordx4 v[118:121], v[12:13], off offset:768
	global_load_dwordx4 v[122:125], v[16:17], off offset:768
	global_load_dwordx4 v[162:165], v[14:15], off offset:768
	ds_read_b128 v[178:181], v45 offset:16640
	ds_read_b128 v[194:197], v46 offset:49408
	ds_read_b128 v[198:201], v45 offset:18688
	ds_read_b128 v[202:205], v46 offset:51456
	ds_read_b128 v[206:209], v46 offset:53504
	ds_read_b128 v[210:213], v46 offset:55552
	s_waitcnt lgkmcnt(4)
	v_mfma_f32_16x16x32_bf16 v[142:145], v[178:181], v[194:197], v[142:145]
	s_waitcnt lgkmcnt(2)
	v_mfma_f32_16x16x32_bf16 v[146:149], v[178:181], v[202:205], v[146:149]
	s_waitcnt lgkmcnt(1)
	v_mfma_f32_16x16x32_bf16 v[158:161], v[178:181], v[206:209], v[158:161]
	s_waitcnt lgkmcnt(0)
	v_mfma_f32_16x16x32_bf16 v[26:29], v[178:181], v[210:213], v[26:29]
	v_mfma_f32_16x16x32_bf16 v[86:89], v[198:201], v[194:197], v[86:89]
	v_mfma_f32_16x16x32_bf16 v[102:105], v[198:201], v[202:205], v[102:105]
	v_mfma_f32_16x16x32_bf16 v[126:129], v[198:201], v[206:209], v[126:129]
	v_mfma_f32_16x16x32_bf16 v[54:57], v[198:201], v[210:213], v[54:57]
	ds_read_b128 v[178:181], v45 offset:20736
	ds_read_b128 v[198:201], v45 offset:22784
	s_waitcnt vmcnt(23)
	ds_write_b128 v35, v[70:73] offset:256
	s_waitcnt vmcnt(21)
	ds_write_b128 v35, v[78:81] offset:4352
	s_waitcnt vmcnt(19)
	ds_write_b128 v35, v[150:153] offset:8448
	s_waitcnt vmcnt(17)
	ds_write_b128 v35, v[170:173] offset:12544
	s_waitcnt lgkmcnt(5)
	v_mfma_f32_16x16x32_bf16 v[182:185], v[178:181], v[194:197], v[182:185]
	v_mfma_f32_16x16x32_bf16 v[186:189], v[178:181], v[202:205], v[186:189]
	v_mfma_f32_16x16x32_bf16 v[190:193], v[178:181], v[206:209], v[190:193]
	v_mfma_f32_16x16x32_bf16 v[110:113], v[178:181], v[210:213], v[110:113]
	s_waitcnt lgkmcnt(4)
	v_mfma_f32_16x16x32_bf16 v[40:43], v[198:201], v[194:197], v[40:43]
	v_mfma_f32_16x16x32_bf16 v[62:65], v[198:201], v[202:205], v[62:65]
	v_mfma_f32_16x16x32_bf16 v[106:109], v[198:201], v[206:209], v[106:109]
	v_mfma_f32_16x16x32_bf16 v[18:21], v[198:201], v[210:213], v[18:21]
	ds_read_b128 v[70:73], v47 offset:16640
	ds_read_b128 v[78:81], v48 offset:49408
	ds_read_b128 v[150:153], v47 offset:18688
	ds_read_b128 v[170:173], v48 offset:51456
	ds_read_b128 v[178:181], v48 offset:53504
	ds_read_b128 v[194:197], v48 offset:55552
	s_waitcnt lgkmcnt(4)
	v_mfma_f32_16x16x32_bf16 v[142:145], v[70:73], v[78:81], v[142:145]
	s_waitcnt lgkmcnt(2)
	v_mfma_f32_16x16x32_bf16 v[146:149], v[70:73], v[170:173], v[146:149]
	s_waitcnt lgkmcnt(1)
	v_mfma_f32_16x16x32_bf16 v[158:161], v[70:73], v[178:181], v[158:161]
	s_waitcnt lgkmcnt(0)
	v_mfma_f32_16x16x32_bf16 v[26:29], v[70:73], v[194:197], v[26:29]
	v_mfma_f32_16x16x32_bf16 v[70:73], v[150:153], v[78:81], v[86:89]
	v_mfma_f32_16x16x32_bf16 v[86:89], v[150:153], v[170:173], v[102:105]
	v_mfma_f32_16x16x32_bf16 v[102:105], v[150:153], v[178:181], v[126:129]
	v_mfma_f32_16x16x32_bf16 v[54:57], v[150:153], v[194:197], v[54:57]
	s_nop 1
	ds_read_b128 v[126:129], v47 offset:20736
	ds_read_b128 v[150:153], v47 offset:22784
	ds_write_b128 v35, v[74:77] offset:33024
	ds_write_b128 v35, v[82:85] offset:37120
	ds_write_b128 v35, v[154:157] offset:41216
	s_waitcnt vmcnt(16)
	ds_write_b128 v35, v[174:177] offset:45312
	s_waitcnt lgkmcnt(5)
	v_mfma_f32_16x16x32_bf16 v[182:185], v[126:129], v[78:81], v[182:185]
	v_mfma_f32_16x16x32_bf16 v[186:189], v[126:129], v[170:173], v[186:189]
	v_mfma_f32_16x16x32_bf16 v[190:193], v[126:129], v[178:181], v[190:193]
	v_mfma_f32_16x16x32_bf16 v[110:113], v[126:129], v[194:197], v[110:113]
	s_waitcnt lgkmcnt(4)
	v_mfma_f32_16x16x32_bf16 v[40:43], v[150:153], v[78:81], v[40:43]
	v_mfma_f32_16x16x32_bf16 v[62:65], v[150:153], v[170:173], v[62:65]
	v_mfma_f32_16x16x32_bf16 v[78:81], v[150:153], v[178:181], v[106:109]
	v_mfma_f32_16x16x32_bf16 v[18:21], v[150:153], v[194:197], v[18:21]
	s_waitcnt lgkmcnt(0)
	s_barrier
; #define MFMA16(a, b, c) __builtin_amdgcn_mfma_f32_16x16x32_bf16((a), (b), (c), 0, 0, 0)
; DI void gemm_mainloop(const u16* __restrict__ A, const u16* __restrict__ Bt, int tm, int tn, char* smem, f32x4 (&acc)[4][4]) {
;     ...
; #pragma unroll
;   for (int kt = 0; kt < 16; kt++) {
;     const int cur = kt & 1;
;     if (kt + 3 < 16) {
; #pragma unroll
;       for (int i = 0; i < 4; i++) {
;         ra[kt % 3][i] = *(const u32x4*)(Ag + (size_t)(32 * i) * 1024 + (kt + 3) * 64);
;         rb[kt % 3][i] = *(const u32x4*)(Bg + (size_t)(32 * i) * 1024 + (kt + 3) * 64);
;       }
;     }
;     __builtin_amdgcn_sched_barrier(0);
;     const char* Ac = As + cur * 16384; const char* Bc = Bs + cur * 16384;
; #pragma unroll
;     for (int ks = 0; ks < 2; ks++) {
;       bf16x8 af[4], bfr[4];
; #pragma unroll
;       for (int mt = 0; mt < 4; mt++) af[mt] = ldfrag(Ac, gswz(wm * 64 + mt * 16 + l15, ks * 4 + g));
; #pragma unroll
;       for (int nt = 0; nt < 4; nt++) bfr[nt] = ldfrag(Bc, gswz(wn * 64 + nt * 16 + l15, ks * 4 + g));
; #pragma unroll
;       for (int mt = 0; mt < 4; mt++)
; #pragma unroll
;         for (int nt = 0; nt < 4; nt++) acc[mt][nt] = MFMA16(af[mt], bfr[nt], acc[mt][nt]);
;       if (kt + 1 < 16) {
;         char* Xn = (ks == 0 ? As : Bs) + (cur ^ 1) * 16384;
; #pragma unroll
;         for (int i = 0; i < 4; i++) *(u32x4*)(Xn + gswz(lrow + 32 * i, lch)) = (ks == 0 ? ra[(kt + 1) % 3][i] : rb[(kt + 1) % 3][i]);
;       }
;       __builtin_amdgcn_sched_barrier(0);
;     }
;     __syncthreads();
;   }
	global_load_dwordx4 v[74:77], v[2:3], off offset:896
	global_load_dwordx4 v[82:85], v[4:5], off offset:896
	global_load_dwordx4 v[106:109], v[6:7], off offset:896
	global_load_dwordx4 v[126:129], v[8:9], off offset:896
	global_load_dwordx4 v[150:153], v[10:11], off offset:896
	global_load_dwordx4 v[154:157], v[12:13], off offset:896
	global_load_dwordx4 v[170:173], v[16:17], off offset:896
	global_load_dwordx4 v[174:177], v[14:15], off offset:896
	ds_read_b128 v[178:181], v45 offset:256
	ds_read_b128 v[194:197], v46 offset:33024
	ds_read_b128 v[198:201], v45 offset:2304
	ds_read_b128 v[202:205], v46 offset:35072
	ds_read_b128 v[206:209], v46 offset:37120
	ds_read_b128 v[210:213], v46 offset:39168
	s_waitcnt lgkmcnt(4)
	v_mfma_f32_16x16x32_bf16 v[142:145], v[178:181], v[194:197], v[142:145]
	s_waitcnt lgkmcnt(2)
	v_mfma_f32_16x16x32_bf16 v[146:149], v[178:181], v[202:205], v[146:149]
	s_waitcnt lgkmcnt(1)
	v_mfma_f32_16x16x32_bf16 v[158:161], v[178:181], v[206:209], v[158:161]
	s_waitcnt lgkmcnt(0)
	v_mfma_f32_16x16x32_bf16 v[26:29], v[178:181], v[210:213], v[26:29]
	v_mfma_f32_16x16x32_bf16 v[70:73], v[198:201], v[194:197], v[70:73]
	v_mfma_f32_16x16x32_bf16 v[86:89], v[198:201], v[202:205], v[86:89]
	v_mfma_f32_16x16x32_bf16 v[102:105], v[198:201], v[206:209], v[102:105]
	v_mfma_f32_16x16x32_bf16 v[54:57], v[198:201], v[210:213], v[54:57]
	ds_read_b128 v[178:181], v45 offset:4352
	ds_read_b128 v[198:201], v45 offset:6400
	s_waitcnt vmcnt(23)
	ds_write_b128 v35, v[66:69] offset:16640
	s_waitcnt vmcnt(21)
	ds_write_b128 v35, v[94:97] offset:20736
	s_waitcnt vmcnt(19)
	ds_write_b128 v35, v[130:133] offset:24832
	s_waitcnt vmcnt(17)
	ds_write_b128 v35, v[138:141] offset:28928
	s_waitcnt lgkmcnt(5)
	v_mfma_f32_16x16x32_bf16 v[182:185], v[178:181], v[194:197], v[182:185]
	v_mfma_f32_16x16x32_bf16 v[186:189], v[178:181], v[202:205], v[186:189]
	v_mfma_f32_16x16x32_bf16 v[190:193], v[178:181], v[206:209], v[190:193]
	v_mfma_f32_16x16x32_bf16 v[110:113], v[178:181], v[210:213], v[110:113]
	s_waitcnt lgkmcnt(4)
	v_mfma_f32_16x16x32_bf16 v[40:43], v[198:201], v[194:197], v[40:43]
	v_mfma_f32_16x16x32_bf16 v[62:65], v[198:201], v[202:205], v[62:65]
	v_mfma_f32_16x16x32_bf16 v[78:81], v[198:201], v[206:209], v[78:81]
	v_mfma_f32_16x16x32_bf16 v[18:21], v[198:201], v[210:213], v[18:21]
	ds_read_b128 v[66:69], v47 offset:256
	ds_read_b128 v[94:97], v48 offset:33024
	ds_read_b128 v[130:133], v47 offset:2304
	ds_read_b128 v[138:141], v48 offset:35072
	ds_read_b128 v[178:181], v48 offset:37120
	ds_read_b128 v[194:197], v48 offset:39168
	s_waitcnt lgkmcnt(4)
	v_mfma_f32_16x16x32_bf16 v[142:145], v[66:69], v[94:97], v[142:145]
	s_waitcnt lgkmcnt(2)
	v_mfma_f32_16x16x32_bf16 v[146:149], v[66:69], v[138:141], v[146:149]
	s_waitcnt lgkmcnt(1)
	v_mfma_f32_16x16x32_bf16 v[158:161], v[66:69], v[178:181], v[158:161]
	s_waitcnt lgkmcnt(0)
	v_mfma_f32_16x16x32_bf16 v[26:29], v[66:69], v[194:197], v[26:29]
	v_mfma_f32_16x16x32_bf16 v[66:69], v[130:133], v[94:97], v[70:73]
	v_mfma_f32_16x16x32_bf16 v[70:73], v[130:133], v[138:141], v[86:89]
	v_mfma_f32_16x16x32_bf16 v[86:89], v[130:133], v[178:181], v[102:105]
	v_mfma_f32_16x16x32_bf16 v[54:57], v[130:133], v[194:197], v[54:57]
	s_nop 1
	ds_read_b128 v[102:105], v47 offset:4352
	ds_read_b128 v[130:133], v47 offset:6400
	ds_write_b128 v35, v[90:93] offset:49408
	ds_write_b128 v35, v[98:101] offset:53504
	ds_write_b128 v35, v[134:137] offset:57600
	s_waitcnt vmcnt(16)
	ds_write_b128 v35, v[166:169] offset:61696
	s_waitcnt lgkmcnt(5)
	v_mfma_f32_16x16x32_bf16 v[182:185], v[102:105], v[94:97], v[182:185]
	v_mfma_f32_16x16x32_bf16 v[186:189], v[102:105], v[138:141], v[186:189]
	v_mfma_f32_16x16x32_bf16 v[190:193], v[102:105], v[178:181], v[190:193]
	v_mfma_f32_16x16x32_bf16 v[102:105], v[102:105], v[194:197], v[110:113]
	s_waitcnt lgkmcnt(4)
	v_mfma_f32_16x16x32_bf16 v[40:43], v[130:133], v[94:97], v[40:43]
	v_mfma_f32_16x16x32_bf16 v[62:65], v[130:133], v[138:141], v[62:65]
	v_mfma_f32_16x16x32_bf16 v[78:81], v[130:133], v[178:181], v[78:81]
	v_mfma_f32_16x16x32_bf16 v[18:21], v[130:133], v[194:197], v[18:21]
	s_waitcnt lgkmcnt(0)
	s_barrier
	global_load_dwordx4 v[90:93], v[2:3], off offset:1024
	global_load_dwordx4 v[94:97], v[4:5], off offset:1024
	global_load_dwordx4 v[98:101], v[6:7], off offset:1024
	global_load_dwordx4 v[110:113], v[8:9], off offset:1024
	global_load_dwordx4 v[130:133], v[10:11], off offset:1024
	global_load_dwordx4 v[134:137], v[12:13], off offset:1024
	global_load_dwordx4 v[138:141], v[16:17], off offset:1024
	global_load_dwordx4 v[166:169], v[14:15], off offset:1024
	ds_read_b128 v[178:181], v45 offset:16640
	ds_read_b128 v[194:197], v46 offset:49408
	ds_read_b128 v[198:201], v45 offset:18688
	ds_read_b128 v[202:205], v46 offset:51456
	ds_read_b128 v[206:209], v46 offset:53504
	ds_read_b128 v[210:213], v46 offset:55552
	s_waitcnt lgkmcnt(4)
	v_mfma_f32_16x16x32_bf16 v[142:145], v[178:181], v[194:197], v[142:145]
	s_waitcnt lgkmcnt(2)
	v_mfma_f32_16x16x32_bf16 v[146:149], v[178:181], v[202:205], v[146:149]
	s_waitcnt lgkmcnt(1)
	v_mfma_f32_16x16x32_bf16 v[158:161], v[178:181], v[206:209], v[158:161]
	s_waitcnt lgkmcnt(0)
	v_mfma_f32_16x16x32_bf16 v[26:29], v[178:181], v[210:213], v[26:29]
	v_mfma_f32_16x16x32_bf16 v[66:69], v[198:201], v[194:197], v[66:69]
	v_mfma_f32_16x16x32_bf16 v[70:73], v[198:201], v[202:205], v[70:73]
	v_mfma_f32_16x16x32_bf16 v[86:89], v[198:201], v[206:209], v[86:89]
	v_mfma_f32_16x16x32_bf16 v[54:57], v[198:201], v[210:213], v[54:57]
	ds_read_b128 v[178:181], v45 offset:20736
	ds_read_b128 v[198:201], v45 offset:22784
	s_waitcnt vmcnt(23)
; #define MFMA16(a, b, c) __builtin_amdgcn_mfma_f32_16x16x32_bf16((a), (b), (c), 0, 0, 0)
; DI void gemm_mainloop(const u16* __restrict__ A, const u16* __restrict__ Bt, int tm, int tn, char* smem, f32x4 (&acc)[4][4]) {
;     ...
; #pragma unroll
;   for (int kt = 0; kt < 16; kt++) {
;     const int cur = kt & 1;
;     if (kt + 3 < 16) {
; #pragma unroll
;       for (int i = 0; i < 4; i++) {
;         ra[kt % 3][i] = *(const u32x4*)(Ag + (size_t)(32 * i) * 1024 + (kt + 3) * 64);
;         rb[kt % 3][i] = *(const u32x4*)(Bg + (size_t)(32 * i) * 1024 + (kt + 3) * 64);
;       }
;     }
;     __builtin_amdgcn_sched_barrier(0);
;     const char* Ac = As + cur * 16384; const char* Bc = Bs + cur * 16384;
; #pragma unroll
;     for (int ks = 0; ks < 2; ks++) {
;       bf16x8 af[4], bfr[4];
; #pragma unroll
;       for (int mt = 0; mt < 4; mt++) af[mt] = ldfrag(Ac, gswz(wm * 64 + mt * 16 + l15, ks * 4 + g));
; #pragma unroll
;       for (int nt = 0; nt < 4; nt++) bfr[nt] = ldfrag(Bc, gswz(wn * 64 + nt * 16 + l15, ks * 4 + g));
; #pragma unroll
;       for (int mt = 0; mt < 4; mt++)
; #pragma unroll
;         for (int nt = 0; nt < 4; nt++) acc[mt][nt] = MFMA16(af[mt], bfr[nt], acc[mt][nt]);
;       if (kt + 1 < 16) {
;         char* Xn = (ks == 0 ? As : Bs) + (cur ^ 1) * 16384;
; #pragma unroll
;         for (int i = 0; i < 4; i++) *(u32x4*)(Xn + gswz(lrow + 32 * i, lch)) = (ks == 0 ? ra[(kt + 1) % 3][i] : rb[(kt + 1) % 3][i]);
;       }
;       __builtin_amdgcn_sched_barrier(0);
;     }
;     __syncthreads();
;   }
	ds_write_b128 v35, v[22:25] offset:256
	s_waitcnt vmcnt(21)
	ds_write_b128 v35, v[50:53] offset:4352
	s_waitcnt vmcnt(19)
	ds_write_b128 v35, v[114:117] offset:8448
	s_waitcnt vmcnt(17)
	ds_write_b128 v35, v[122:125] offset:12544
	s_waitcnt lgkmcnt(5)
	v_mfma_f32_16x16x32_bf16 v[182:185], v[178:181], v[194:197], v[182:185]
	v_mfma_f32_16x16x32_bf16 v[186:189], v[178:181], v[202:205], v[186:189]
	v_mfma_f32_16x16x32_bf16 v[190:193], v[178:181], v[206:209], v[190:193]
	v_mfma_f32_16x16x32_bf16 v[102:105], v[178:181], v[210:213], v[102:105]
	s_waitcnt lgkmcnt(4)
	v_mfma_f32_16x16x32_bf16 v[40:43], v[198:201], v[194:197], v[40:43]
	v_mfma_f32_16x16x32_bf16 v[62:65], v[198:201], v[202:205], v[62:65]
	v_mfma_f32_16x16x32_bf16 v[78:81], v[198:201], v[206:209], v[78:81]
	v_mfma_f32_16x16x32_bf16 v[18:21], v[198:201], v[210:213], v[18:21]
	ds_read_b128 v[22:25], v47 offset:16640
	ds_read_b128 v[50:53], v48 offset:49408
	ds_read_b128 v[114:117], v47 offset:18688
	ds_read_b128 v[122:125], v48 offset:51456
	ds_read_b128 v[178:181], v48 offset:53504
	ds_read_b128 v[194:197], v48 offset:55552
	s_waitcnt lgkmcnt(4)
	v_mfma_f32_16x16x32_bf16 v[142:145], v[22:25], v[50:53], v[142:145]
	s_waitcnt lgkmcnt(2)
	v_mfma_f32_16x16x32_bf16 v[146:149], v[22:25], v[122:125], v[146:149]
	s_waitcnt lgkmcnt(1)
	v_mfma_f32_16x16x32_bf16 v[158:161], v[22:25], v[178:181], v[158:161]
	s_waitcnt lgkmcnt(0)
	v_mfma_f32_16x16x32_bf16 v[22:25], v[22:25], v[194:197], v[26:29]
	v_mfma_f32_16x16x32_bf16 v[26:29], v[114:117], v[50:53], v[66:69]
	v_mfma_f32_16x16x32_bf16 v[66:69], v[114:117], v[122:125], v[70:73]
	v_mfma_f32_16x16x32_bf16 v[70:73], v[114:117], v[178:181], v[86:89]
	v_mfma_f32_16x16x32_bf16 v[54:57], v[114:117], v[194:197], v[54:57]
	s_nop 1
	ds_read_b128 v[86:89], v47 offset:20736
	ds_read_b128 v[114:117], v47 offset:22784
	ds_write_b128 v35, v[30:33] offset:33024
	ds_write_b128 v35, v[58:61] offset:37120
	ds_write_b128 v35, v[118:121] offset:41216
	s_waitcnt vmcnt(16)
	ds_write_b128 v35, v[162:165] offset:45312
	s_waitcnt lgkmcnt(5)
	v_mfma_f32_16x16x32_bf16 v[182:185], v[86:89], v[50:53], v[182:185]
	v_mfma_f32_16x16x32_bf16 v[186:189], v[86:89], v[122:125], v[186:189]
	v_mfma_f32_16x16x32_bf16 v[190:193], v[86:89], v[178:181], v[190:193]
	v_mfma_f32_16x16x32_bf16 v[86:89], v[86:89], v[194:197], v[102:105]
	s_waitcnt lgkmcnt(4)
	v_mfma_f32_16x16x32_bf16 v[40:43], v[114:117], v[50:53], v[40:43]
	v_mfma_f32_16x16x32_bf16 v[50:53], v[114:117], v[122:125], v[62:65]
	v_mfma_f32_16x16x32_bf16 v[62:65], v[114:117], v[178:181], v[78:81]
	v_mfma_f32_16x16x32_bf16 v[18:21], v[114:117], v[194:197], v[18:21]
	s_waitcnt lgkmcnt(0)
	s_barrier
	global_load_dwordx4 v[30:33], v[2:3], off offset:1152
	global_load_dwordx4 v[58:61], v[4:5], off offset:1152
	global_load_dwordx4 v[78:81], v[6:7], off offset:1152
	global_load_dwordx4 v[102:105], v[8:9], off offset:1152
	global_load_dwordx4 v[114:117], v[10:11], off offset:1152
	global_load_dwordx4 v[118:121], v[12:13], off offset:1152
	global_load_dwordx4 v[122:125], v[16:17], off offset:1152
	global_load_dwordx4 v[162:165], v[14:15], off offset:1152
	ds_read_b128 v[178:181], v45 offset:256
	ds_read_b128 v[194:197], v46 offset:33024
	ds_read_b128 v[198:201], v45 offset:2304
	ds_read_b128 v[202:205], v46 offset:35072
	ds_read_b128 v[206:209], v46 offset:37120
	ds_read_b128 v[210:213], v46 offset:39168
	s_waitcnt lgkmcnt(4)
	v_mfma_f32_16x16x32_bf16 v[142:145], v[178:181], v[194:197], v[142:145]
	s_waitcnt lgkmcnt(2)
	v_mfma_f32_16x16x32_bf16 v[146:149], v[178:181], v[202:205], v[146:149]
	s_waitcnt lgkmcnt(1)
	v_mfma_f32_16x16x32_bf16 v[158:161], v[178:181], v[206:209], v[158:161]
	s_waitcnt lgkmcnt(0)
	v_mfma_f32_16x16x32_bf16 v[22:25], v[178:181], v[210:213], v[22:25]
	v_mfma_f32_16x16x32_bf16 v[26:29], v[198:201], v[194:197], v[26:29]
	v_mfma_f32_16x16x32_bf16 v[66:69], v[198:201], v[202:205], v[66:69]
	v_mfma_f32_16x16x32_bf16 v[70:73], v[198:201], v[206:209], v[70:73]
	v_mfma_f32_16x16x32_bf16 v[54:57], v[198:201], v[210:213], v[54:57]
	ds_read_b128 v[178:181], v45 offset:4352
	ds_read_b128 v[198:201], v45 offset:6400
	s_waitcnt vmcnt(23)
	ds_write_b128 v35, v[74:77] offset:16640
	s_waitcnt vmcnt(21)
	ds_write_b128 v35, v[106:109] offset:20736
	s_waitcnt vmcnt(19)
	ds_write_b128 v35, v[150:153] offset:24832
	s_waitcnt vmcnt(17)
	ds_write_b128 v35, v[170:173] offset:28928
	s_waitcnt lgkmcnt(5)
	v_mfma_f32_16x16x32_bf16 v[182:185], v[178:181], v[194:197], v[182:185]
	v_mfma_f32_16x16x32_bf16 v[186:189], v[178:181], v[202:205], v[186:189]
	v_mfma_f32_16x16x32_bf16 v[190:193], v[178:181], v[206:209], v[190:193]
	v_mfma_f32_16x16x32_bf16 v[86:89], v[178:181], v[210:213], v[86:89]
	s_waitcnt lgkmcnt(4)
	v_mfma_f32_16x16x32_bf16 v[40:43], v[198:201], v[194:197], v[40:43]
	v_mfma_f32_16x16x32_bf16 v[50:53], v[198:201], v[202:205], v[50:53]
	v_mfma_f32_16x16x32_bf16 v[62:65], v[198:201], v[206:209], v[62:65]
	v_mfma_f32_16x16x32_bf16 v[18:21], v[198:201], v[210:213], v[18:21]
	ds_read_b128 v[74:77], v47 offset:256
	ds_read_b128 v[106:109], v48 offset:33024
	ds_read_b128 v[150:153], v47 offset:2304
	ds_read_b128 v[170:173], v48 offset:35072
	ds_read_b128 v[178:181], v48 offset:37120
	ds_read_b128 v[194:197], v48 offset:39168
	s_waitcnt lgkmcnt(4)
	v_mfma_f32_16x16x32_bf16 v[142:145], v[74:77], v[106:109], v[142:145]
	s_waitcnt lgkmcnt(2)
	v_mfma_f32_16x16x32_bf16 v[146:149], v[74:77], v[170:173], v[146:149]
	s_waitcnt lgkmcnt(1)
	v_mfma_f32_16x16x32_bf16 v[158:161], v[74:77], v[178:181], v[158:161]
	s_waitcnt lgkmcnt(0)
	v_mfma_f32_16x16x32_bf16 v[22:25], v[74:77], v[194:197], v[22:25]
	v_mfma_f32_16x16x32_bf16 v[26:29], v[150:153], v[106:109], v[26:29]
	v_mfma_f32_16x16x32_bf16 v[66:69], v[150:153], v[170:173], v[66:69]
	v_mfma_f32_16x16x32_bf16 v[70:73], v[150:153], v[178:181], v[70:73]
	v_mfma_f32_16x16x32_bf16 v[54:57], v[150:153], v[194:197], v[54:57]
	ds_read_b128 v[74:77], v47 offset:4352
	ds_read_b128 v[150:153], v47 offset:6400
	ds_write_b128 v35, v[82:85] offset:49408
	ds_write_b128 v35, v[126:129] offset:53504
	ds_write_b128 v35, v[154:157] offset:57600
	s_waitcnt vmcnt(16)
	ds_write_b128 v35, v[174:177] offset:61696
	s_waitcnt lgkmcnt(5)
	v_mfma_f32_16x16x32_bf16 v[182:185], v[74:77], v[106:109], v[182:185]
	v_mfma_f32_16x16x32_bf16 v[186:189], v[74:77], v[170:173], v[186:189]
	v_mfma_f32_16x16x32_bf16 v[190:193], v[74:77], v[178:181], v[190:193]
	v_mfma_f32_16x16x32_bf16 v[74:77], v[74:77], v[194:197], v[86:89]
	s_waitcnt lgkmcnt(4)
	v_mfma_f32_16x16x32_bf16 v[40:43], v[150:153], v[106:109], v[40:43]
	v_mfma_f32_16x16x32_bf16 v[50:53], v[150:153], v[170:173], v[50:53]
	v_mfma_f32_16x16x32_bf16 v[62:65], v[150:153], v[178:181], v[62:65]
	v_mfma_f32_16x16x32_bf16 v[18:21], v[150:153], v[194:197], v[18:21]
	s_waitcnt lgkmcnt(0)
	s_barrier
; #define MFMA16(a, b, c) __builtin_amdgcn_mfma_f32_16x16x32_bf16((a), (b), (c), 0, 0, 0)
; DI void gemm_mainloop(const u16* __restrict__ A, const u16* __restrict__ Bt, int tm, int tn, char* smem, f32x4 (&acc)[4][4]) {
;     ...
; #pragma unroll
;   for (int kt = 0; kt < 16; kt++) {
;     const int cur = kt & 1;
;     if (kt + 3 < 16) {
; #pragma unroll
;       for (int i = 0; i < 4; i++) {
;         ra[kt % 3][i] = *(const u32x4*)(Ag + (size_t)(32 * i) * 1024 + (kt + 3) * 64);
;         rb[kt % 3][i] = *(const u32x4*)(Bg + (size_t)(32 * i) * 1024 + (kt + 3) * 64);
;       }
;     }
;     __builtin_amdgcn_sched_barrier(0);
;     const char* Ac = As + cur * 16384; const char* Bc = Bs + cur * 16384;
; #pragma unroll
;     for (int ks = 0; ks < 2; ks++) {
;       bf16x8 af[4], bfr[4];
; #pragma unroll
;       for (int mt = 0; mt < 4; mt++) af[mt] = ldfrag(Ac, gswz(wm * 64 + mt * 16 + l15, ks * 4 + g));
; #pragma unroll
;       for (int nt = 0; nt < 4; nt++) bfr[nt] = ldfrag(Bc, gswz(wn * 64 + nt * 16 + l15, ks * 4 + g));
; #pragma unroll
;       for (int mt = 0; mt < 4; mt++)
; #pragma unroll
;         for (int nt = 0; nt < 4; nt++) acc[mt][nt] = MFMA16(af[mt], bfr[nt], acc[mt][nt]);
;       if (kt + 1 < 16) {
;         char* Xn = (ks == 0 ? As : Bs) + (cur ^ 1) * 16384;
; #pragma unroll
;         for (int i = 0; i < 4; i++) *(u32x4*)(Xn + gswz(lrow + 32 * i, lch)) = (ks == 0 ? ra[(kt + 1) % 3][i] : rb[(kt + 1) % 3][i]);
;       }
;       __builtin_amdgcn_sched_barrier(0);
;     }
;     __syncthreads();
;   }
	global_load_dwordx4 v[82:85], v[2:3], off offset:1280
	global_load_dwordx4 v[86:89], v[4:5], off offset:1280
	global_load_dwordx4 v[106:109], v[6:7], off offset:1280
	global_load_dwordx4 v[126:129], v[8:9], off offset:1280
	global_load_dwordx4 v[150:153], v[10:11], off offset:1280
	global_load_dwordx4 v[154:157], v[12:13], off offset:1280
	global_load_dwordx4 v[170:173], v[16:17], off offset:1280
	global_load_dwordx4 v[174:177], v[14:15], off offset:1280
	ds_read_b128 v[178:181], v45 offset:16640
	ds_read_b128 v[194:197], v46 offset:49408
	ds_read_b128 v[198:201], v45 offset:18688
	ds_read_b128 v[202:205], v46 offset:51456
	ds_read_b128 v[206:209], v46 offset:53504
	ds_read_b128 v[210:213], v46 offset:55552
	s_waitcnt lgkmcnt(4)
	v_mfma_f32_16x16x32_bf16 v[142:145], v[178:181], v[194:197], v[142:145]
	s_waitcnt lgkmcnt(2)
	v_mfma_f32_16x16x32_bf16 v[146:149], v[178:181], v[202:205], v[146:149]
	s_waitcnt lgkmcnt(1)
	v_mfma_f32_16x16x32_bf16 v[158:161], v[178:181], v[206:209], v[158:161]
	s_waitcnt lgkmcnt(0)
	v_mfma_f32_16x16x32_bf16 v[22:25], v[178:181], v[210:213], v[22:25]
	v_mfma_f32_16x16x32_bf16 v[26:29], v[198:201], v[194:197], v[26:29]
	v_mfma_f32_16x16x32_bf16 v[66:69], v[198:201], v[202:205], v[66:69]
	v_mfma_f32_16x16x32_bf16 v[70:73], v[198:201], v[206:209], v[70:73]
	v_mfma_f32_16x16x32_bf16 v[54:57], v[198:201], v[210:213], v[54:57]
	ds_read_b128 v[178:181], v45 offset:20736
	ds_read_b128 v[198:201], v45 offset:22784
	s_waitcnt vmcnt(23)
	ds_write_b128 v35, v[90:93] offset:256
	s_waitcnt vmcnt(21)
	ds_write_b128 v35, v[98:101] offset:4352
	s_waitcnt vmcnt(19)
	ds_write_b128 v35, v[130:133] offset:8448
	s_waitcnt vmcnt(17)
	ds_write_b128 v35, v[138:141] offset:12544
	s_waitcnt lgkmcnt(5)
	v_mfma_f32_16x16x32_bf16 v[182:185], v[178:181], v[194:197], v[182:185]
	v_mfma_f32_16x16x32_bf16 v[186:189], v[178:181], v[202:205], v[186:189]
	v_mfma_f32_16x16x32_bf16 v[190:193], v[178:181], v[206:209], v[190:193]
	v_mfma_f32_16x16x32_bf16 v[74:77], v[178:181], v[210:213], v[74:77]
	s_waitcnt lgkmcnt(4)
	v_mfma_f32_16x16x32_bf16 v[40:43], v[198:201], v[194:197], v[40:43]
	v_mfma_f32_16x16x32_bf16 v[50:53], v[198:201], v[202:205], v[50:53]
	v_mfma_f32_16x16x32_bf16 v[62:65], v[198:201], v[206:209], v[62:65]
	v_mfma_f32_16x16x32_bf16 v[18:21], v[198:201], v[210:213], v[18:21]
	ds_read_b128 v[90:93], v47 offset:16640
	ds_read_b128 v[98:101], v48 offset:49408
	ds_read_b128 v[130:133], v47 offset:18688
	ds_read_b128 v[138:141], v48 offset:51456
	ds_read_b128 v[178:181], v48 offset:53504
	ds_read_b128 v[194:197], v48 offset:55552
	s_waitcnt lgkmcnt(4)
	v_mfma_f32_16x16x32_bf16 v[142:145], v[90:93], v[98:101], v[142:145]
	s_waitcnt lgkmcnt(2)
	v_mfma_f32_16x16x32_bf16 v[146:149], v[90:93], v[138:141], v[146:149]
	s_waitcnt lgkmcnt(1)
	v_mfma_f32_16x16x32_bf16 v[158:161], v[90:93], v[178:181], v[158:161]
	s_waitcnt lgkmcnt(0)
	v_mfma_f32_16x16x32_bf16 v[22:25], v[90:93], v[194:197], v[22:25]
	v_mfma_f32_16x16x32_bf16 v[26:29], v[130:133], v[98:101], v[26:29]
	v_mfma_f32_16x16x32_bf16 v[66:69], v[130:133], v[138:141], v[66:69]
	v_mfma_f32_16x16x32_bf16 v[70:73], v[130:133], v[178:181], v[70:73]
	v_mfma_f32_16x16x32_bf16 v[54:57], v[130:133], v[194:197], v[54:57]
	ds_read_b128 v[90:93], v47 offset:20736
	ds_read_b128 v[130:133], v47 offset:22784
	ds_write_b128 v35, v[94:97] offset:33024
	ds_write_b128 v35, v[110:113] offset:37120
	ds_write_b128 v35, v[134:137] offset:41216
	s_waitcnt vmcnt(16)
	ds_write_b128 v35, v[166:169] offset:45312
	s_waitcnt lgkmcnt(5)
	v_mfma_f32_16x16x32_bf16 v[182:185], v[90:93], v[98:101], v[182:185]
	v_mfma_f32_16x16x32_bf16 v[186:189], v[90:93], v[138:141], v[186:189]
	v_mfma_f32_16x16x32_bf16 v[190:193], v[90:93], v[178:181], v[190:193]
	v_mfma_f32_16x16x32_bf16 v[74:77], v[90:93], v[194:197], v[74:77]
	s_waitcnt lgkmcnt(4)
	v_mfma_f32_16x16x32_bf16 v[40:43], v[130:133], v[98:101], v[40:43]
	v_mfma_f32_16x16x32_bf16 v[50:53], v[130:133], v[138:141], v[50:53]
	v_mfma_f32_16x16x32_bf16 v[62:65], v[130:133], v[178:181], v[62:65]
	v_mfma_f32_16x16x32_bf16 v[18:21], v[130:133], v[194:197], v[18:21]
	s_waitcnt lgkmcnt(0)
	s_barrier
	global_load_dwordx4 v[90:93], v[2:3], off offset:1408
	global_load_dwordx4 v[94:97], v[4:5], off offset:1408
	global_load_dwordx4 v[98:101], v[6:7], off offset:1408
	global_load_dwordx4 v[110:113], v[8:9], off offset:1408
	global_load_dwordx4 v[130:133], v[10:11], off offset:1408
	global_load_dwordx4 v[134:137], v[12:13], off offset:1408
	global_load_dwordx4 v[138:141], v[16:17], off offset:1408
	global_load_dwordx4 v[166:169], v[14:15], off offset:1408
	ds_read_b128 v[178:181], v45 offset:256
	ds_read_b128 v[194:197], v46 offset:33024
	ds_read_b128 v[198:201], v45 offset:2304
	ds_read_b128 v[202:205], v46 offset:35072
	ds_read_b128 v[206:209], v46 offset:37120
	ds_read_b128 v[210:213], v46 offset:39168
	s_waitcnt lgkmcnt(4)
	v_mfma_f32_16x16x32_bf16 v[142:145], v[178:181], v[194:197], v[142:145]
	s_waitcnt lgkmcnt(2)
	v_mfma_f32_16x16x32_bf16 v[146:149], v[178:181], v[202:205], v[146:149]
	s_waitcnt lgkmcnt(1)
	v_mfma_f32_16x16x32_bf16 v[158:161], v[178:181], v[206:209], v[158:161]
	s_waitcnt lgkmcnt(0)
	v_mfma_f32_16x16x32_bf16 v[22:25], v[178:181], v[210:213], v[22:25]
	v_mfma_f32_16x16x32_bf16 v[26:29], v[198:201], v[194:197], v[26:29]
	v_mfma_f32_16x16x32_bf16 v[66:69], v[198:201], v[202:205], v[66:69]
	v_mfma_f32_16x16x32_bf16 v[70:73], v[198:201], v[206:209], v[70:73]
	v_mfma_f32_16x16x32_bf16 v[54:57], v[198:201], v[210:213], v[54:57]
	ds_read_b128 v[178:181], v45 offset:4352
	ds_read_b128 v[198:201], v45 offset:6400
	s_waitcnt vmcnt(23)
	ds_write_b128 v35, v[30:33] offset:16640
	s_waitcnt vmcnt(21)
; #define MFMA16(a, b, c) __builtin_amdgcn_mfma_f32_16x16x32_bf16((a), (b), (c), 0, 0, 0)
; DI void gemm_mainloop(const u16* __restrict__ A, const u16* __restrict__ Bt, int tm, int tn, char* smem, f32x4 (&acc)[4][4]) {
;     ...
; #pragma unroll
;   for (int kt = 0; kt < 16; kt++) {
;     const int cur = kt & 1;
;     if (kt + 3 < 16) {
; #pragma unroll
;       for (int i = 0; i < 4; i++) {
;         ra[kt % 3][i] = *(const u32x4*)(Ag + (size_t)(32 * i) * 1024 + (kt + 3) * 64);
;         rb[kt % 3][i] = *(const u32x4*)(Bg + (size_t)(32 * i) * 1024 + (kt + 3) * 64);
;       }
;     }
;     __builtin_amdgcn_sched_barrier(0);
;     const char* Ac = As + cur * 16384; const char* Bc = Bs + cur * 16384;
; #pragma unroll
;     for (int ks = 0; ks < 2; ks++) {
;       bf16x8 af[4], bfr[4];
; #pragma unroll
;       for (int mt = 0; mt < 4; mt++) af[mt] = ldfrag(Ac, gswz(wm * 64 + mt * 16 + l15, ks * 4 + g));
; #pragma unroll
;       for (int nt = 0; nt < 4; nt++) bfr[nt] = ldfrag(Bc, gswz(wn * 64 + nt * 16 + l15, ks * 4 + g));
; #pragma unroll
;       for (int mt = 0; mt < 4; mt++)
; #pragma unroll
;         for (int nt = 0; nt < 4; nt++) acc[mt][nt] = MFMA16(af[mt], bfr[nt], acc[mt][nt]);
;       if (kt + 1 < 16) {
;         char* Xn = (ks == 0 ? As : Bs) + (cur ^ 1) * 16384;
; #pragma unroll
;         for (int i = 0; i < 4; i++) *(u32x4*)(Xn + gswz(lrow + 32 * i, lch)) = (ks == 0 ? ra[(kt + 1) % 3][i] : rb[(kt + 1) % 3][i]);
;       }
;       __builtin_amdgcn_sched_barrier(0);
;     }
;     __syncthreads();
;   }
	ds_write_b128 v35, v[78:81] offset:20736
	s_waitcnt vmcnt(19)
	ds_write_b128 v35, v[114:117] offset:24832
	s_waitcnt vmcnt(17)
	ds_write_b128 v35, v[122:125] offset:28928
	s_waitcnt lgkmcnt(5)
	v_mfma_f32_16x16x32_bf16 v[182:185], v[178:181], v[194:197], v[182:185]
	v_mfma_f32_16x16x32_bf16 v[186:189], v[178:181], v[202:205], v[186:189]
	v_mfma_f32_16x16x32_bf16 v[190:193], v[178:181], v[206:209], v[190:193]
	v_mfma_f32_16x16x32_bf16 v[74:77], v[178:181], v[210:213], v[74:77]
	s_waitcnt lgkmcnt(4)
	v_mfma_f32_16x16x32_bf16 v[40:43], v[198:201], v[194:197], v[40:43]
	v_mfma_f32_16x16x32_bf16 v[50:53], v[198:201], v[202:205], v[50:53]
	v_mfma_f32_16x16x32_bf16 v[62:65], v[198:201], v[206:209], v[62:65]
	v_mfma_f32_16x16x32_bf16 v[18:21], v[198:201], v[210:213], v[18:21]
	ds_read_b128 v[30:33], v47 offset:256
	ds_read_b128 v[78:81], v48 offset:33024
	ds_read_b128 v[114:117], v47 offset:2304
	ds_read_b128 v[122:125], v48 offset:35072
	ds_read_b128 v[178:181], v48 offset:37120
	ds_read_b128 v[194:197], v48 offset:39168
	s_waitcnt lgkmcnt(4)
	v_mfma_f32_16x16x32_bf16 v[142:145], v[30:33], v[78:81], v[142:145]
	s_waitcnt lgkmcnt(2)
	v_mfma_f32_16x16x32_bf16 v[146:149], v[30:33], v[122:125], v[146:149]
	s_waitcnt lgkmcnt(1)
	v_mfma_f32_16x16x32_bf16 v[158:161], v[30:33], v[178:181], v[158:161]
	s_waitcnt lgkmcnt(0)
	v_mfma_f32_16x16x32_bf16 v[22:25], v[30:33], v[194:197], v[22:25]
	v_mfma_f32_16x16x32_bf16 v[26:29], v[114:117], v[78:81], v[26:29]
	v_mfma_f32_16x16x32_bf16 v[30:33], v[114:117], v[122:125], v[66:69]
	v_mfma_f32_16x16x32_bf16 v[66:69], v[114:117], v[178:181], v[70:73]
	v_mfma_f32_16x16x32_bf16 v[54:57], v[114:117], v[194:197], v[54:57]
	s_nop 1
	ds_read_b128 v[70:73], v47 offset:4352
	ds_read_b128 v[114:117], v47 offset:6400
	ds_write_b128 v35, v[58:61] offset:49408
	ds_write_b128 v35, v[102:105] offset:53504
	ds_write_b128 v35, v[118:121] offset:57600
	s_waitcnt vmcnt(16)
	ds_write_b128 v35, v[162:165] offset:61696
	s_waitcnt lgkmcnt(5)
	v_mfma_f32_16x16x32_bf16 v[182:185], v[70:73], v[78:81], v[182:185]
	v_mfma_f32_16x16x32_bf16 v[186:189], v[70:73], v[122:125], v[186:189]
	v_mfma_f32_16x16x32_bf16 v[190:193], v[70:73], v[178:181], v[190:193]
	v_mfma_f32_16x16x32_bf16 v[70:73], v[70:73], v[194:197], v[74:77]
	s_waitcnt lgkmcnt(4)
	v_mfma_f32_16x16x32_bf16 v[40:43], v[114:117], v[78:81], v[40:43]
	v_mfma_f32_16x16x32_bf16 v[50:53], v[114:117], v[122:125], v[50:53]
	v_mfma_f32_16x16x32_bf16 v[62:65], v[114:117], v[178:181], v[62:65]
	v_mfma_f32_16x16x32_bf16 v[18:21], v[114:117], v[194:197], v[18:21]
	s_waitcnt lgkmcnt(0)
	s_barrier
	global_load_dwordx4 v[58:61], v[2:3], off offset:1536
	global_load_dwordx4 v[74:77], v[4:5], off offset:1536
	global_load_dwordx4 v[78:81], v[6:7], off offset:1536
	global_load_dwordx4 v[102:105], v[8:9], off offset:1536
	global_load_dwordx4 v[114:117], v[10:11], off offset:1536
	global_load_dwordx4 v[118:121], v[12:13], off offset:1536
	global_load_dwordx4 v[122:125], v[16:17], off offset:1536
	global_load_dwordx4 v[162:165], v[14:15], off offset:1536
	ds_read_b128 v[178:181], v45 offset:16640
	ds_read_b128 v[194:197], v46 offset:49408
	ds_read_b128 v[198:201], v45 offset:18688
	ds_read_b128 v[202:205], v46 offset:51456
	ds_read_b128 v[206:209], v46 offset:53504
	ds_read_b128 v[210:213], v46 offset:55552
	s_waitcnt lgkmcnt(4)
	v_mfma_f32_16x16x32_bf16 v[142:145], v[178:181], v[194:197], v[142:145]
	s_waitcnt lgkmcnt(2)
	v_mfma_f32_16x16x32_bf16 v[146:149], v[178:181], v[202:205], v[146:149]
	s_waitcnt lgkmcnt(1)
	v_mfma_f32_16x16x32_bf16 v[158:161], v[178:181], v[206:209], v[158:161]
	s_waitcnt lgkmcnt(0)
	v_mfma_f32_16x16x32_bf16 v[22:25], v[178:181], v[210:213], v[22:25]
	v_mfma_f32_16x16x32_bf16 v[26:29], v[198:201], v[194:197], v[26:29]
	v_mfma_f32_16x16x32_bf16 v[30:33], v[198:201], v[202:205], v[30:33]
	v_mfma_f32_16x16x32_bf16 v[66:69], v[198:201], v[206:209], v[66:69]
	v_mfma_f32_16x16x32_bf16 v[54:57], v[198:201], v[210:213], v[54:57]
	ds_read_b128 v[178:181], v45 offset:20736
	ds_read_b128 v[198:201], v45 offset:22784
	s_waitcnt vmcnt(23)
	ds_write_b128 v35, v[82:85] offset:256
	s_waitcnt vmcnt(21)
	ds_write_b128 v35, v[106:109] offset:4352
	s_waitcnt vmcnt(19)
	ds_write_b128 v35, v[150:153] offset:8448
	s_waitcnt vmcnt(17)
	ds_write_b128 v35, v[170:173] offset:12544
	s_waitcnt lgkmcnt(5)
	v_mfma_f32_16x16x32_bf16 v[182:185], v[178:181], v[194:197], v[182:185]
	v_mfma_f32_16x16x32_bf16 v[186:189], v[178:181], v[202:205], v[186:189]
	v_mfma_f32_16x16x32_bf16 v[190:193], v[178:181], v[206:209], v[190:193]
	v_mfma_f32_16x16x32_bf16 v[70:73], v[178:181], v[210:213], v[70:73]
	s_waitcnt lgkmcnt(4)
	v_mfma_f32_16x16x32_bf16 v[40:43], v[198:201], v[194:197], v[40:43]
	v_mfma_f32_16x16x32_bf16 v[50:53], v[198:201], v[202:205], v[50:53]
	v_mfma_f32_16x16x32_bf16 v[62:65], v[198:201], v[206:209], v[62:65]
	v_mfma_f32_16x16x32_bf16 v[18:21], v[198:201], v[210:213], v[18:21]
	ds_read_b128 v[82:85], v47 offset:16640
	ds_read_b128 v[106:109], v48 offset:49408
	ds_read_b128 v[150:153], v47 offset:18688
	ds_read_b128 v[170:173], v48 offset:51456
	ds_read_b128 v[178:181], v48 offset:53504
	ds_read_b128 v[194:197], v48 offset:55552
	s_waitcnt lgkmcnt(4)
	v_mfma_f32_16x16x32_bf16 v[142:145], v[82:85], v[106:109], v[142:145]
	s_waitcnt lgkmcnt(2)
	v_mfma_f32_16x16x32_bf16 v[146:149], v[82:85], v[170:173], v[146:149]
	s_waitcnt lgkmcnt(1)
	v_mfma_f32_16x16x32_bf16 v[158:161], v[82:85], v[178:181], v[158:161]
	s_waitcnt lgkmcnt(0)
	v_mfma_f32_16x16x32_bf16 v[22:25], v[82:85], v[194:197], v[22:25]
	v_mfma_f32_16x16x32_bf16 v[26:29], v[150:153], v[106:109], v[26:29]
	v_mfma_f32_16x16x32_bf16 v[30:33], v[150:153], v[170:173], v[30:33]
	v_mfma_f32_16x16x32_bf16 v[66:69], v[150:153], v[178:181], v[66:69]
	v_mfma_f32_16x16x32_bf16 v[54:57], v[150:153], v[194:197], v[54:57]
	ds_read_b128 v[82:85], v47 offset:20736
	ds_read_b128 v[150:153], v47 offset:22784
	ds_write_b128 v35, v[86:89] offset:33024
	ds_write_b128 v35, v[126:129] offset:37120
	ds_write_b128 v35, v[154:157] offset:41216
	s_waitcnt vmcnt(16)
	ds_write_b128 v35, v[174:177] offset:45312
	s_waitcnt lgkmcnt(5)
	v_mfma_f32_16x16x32_bf16 v[182:185], v[82:85], v[106:109], v[182:185]
	v_mfma_f32_16x16x32_bf16 v[186:189], v[82:85], v[170:173], v[186:189]
	v_mfma_f32_16x16x32_bf16 v[190:193], v[82:85], v[178:181], v[190:193]
	v_mfma_f32_16x16x32_bf16 v[70:73], v[82:85], v[194:197], v[70:73]
	s_waitcnt lgkmcnt(4)
	v_mfma_f32_16x16x32_bf16 v[40:43], v[150:153], v[106:109], v[40:43]
	v_mfma_f32_16x16x32_bf16 v[50:53], v[150:153], v[170:173], v[50:53]
	v_mfma_f32_16x16x32_bf16 v[62:65], v[150:153], v[178:181], v[62:65]
	v_mfma_f32_16x16x32_bf16 v[18:21], v[150:153], v[194:197], v[18:21]
	s_waitcnt lgkmcnt(0)
	s_barrier
; #define MFMA16(a, b, c) __builtin_amdgcn_mfma_f32_16x16x32_bf16((a), (b), (c), 0, 0, 0)
; DI void gemm_mainloop(const u16* __restrict__ A, const u16* __restrict__ Bt, int tm, int tn, char* smem, f32x4 (&acc)[4][4]) {
;     ...
; #pragma unroll
;   for (int kt = 0; kt < 16; kt++) {
;     const int cur = kt & 1;
;     if (kt + 3 < 16) {
; #pragma unroll
;       for (int i = 0; i < 4; i++) {
;         ra[kt % 3][i] = *(const u32x4*)(Ag + (size_t)(32 * i) * 1024 + (kt + 3) * 64);
;         rb[kt % 3][i] = *(const u32x4*)(Bg + (size_t)(32 * i) * 1024 + (kt + 3) * 64);
;       }
;     }
;     __builtin_amdgcn_sched_barrier(0);
;     const char* Ac = As + cur * 16384; const char* Bc = Bs + cur * 16384;
; #pragma unroll
;     for (int ks = 0; ks < 2; ks++) {
;       bf16x8 af[4], bfr[4];
; #pragma unroll
;       for (int mt = 0; mt < 4; mt++) af[mt] = ldfrag(Ac, gswz(wm * 64 + mt * 16 + l15, ks * 4 + g));
; #pragma unroll
;       for (int nt = 0; nt < 4; nt++) bfr[nt] = ldfrag(Bc, gswz(wn * 64 + nt * 16 + l15, ks * 4 + g));
; #pragma unroll
;       for (int mt = 0; mt < 4; mt++)
; #pragma unroll
;         for (int nt = 0; nt < 4; nt++) acc[mt][nt] = MFMA16(af[mt], bfr[nt], acc[mt][nt]);
;       if (kt + 1 < 16) {
;         char* Xn = (ks == 0 ? As : Bs) + (cur ^ 1) * 16384;
; #pragma unroll
;         for (int i = 0; i < 4; i++) *(u32x4*)(Xn + gswz(lrow + 32 * i, lch)) = (ks == 0 ? ra[(kt + 1) % 3][i] : rb[(kt + 1) % 3][i]);
;       }
;       __builtin_amdgcn_sched_barrier(0);
;     }
;     __syncthreads();
;   }
	global_load_dwordx4 v[82:85], v[2:3], off offset:1664
	global_load_dwordx4 v[86:89], v[4:5], off offset:1664
	global_load_dwordx4 v[106:109], v[6:7], off offset:1664
	global_load_dwordx4 v[126:129], v[8:9], off offset:1664
	global_load_dwordx4 v[150:153], v[10:11], off offset:1664
	global_load_dwordx4 v[154:157], v[12:13], off offset:1664
	global_load_dwordx4 v[170:173], v[16:17], off offset:1664
	global_load_dwordx4 v[174:177], v[14:15], off offset:1664
	ds_read_b128 v[178:181], v45 offset:256
	ds_read_b128 v[194:197], v46 offset:33024
	ds_read_b128 v[198:201], v45 offset:2304
	ds_read_b128 v[202:205], v46 offset:35072
	ds_read_b128 v[206:209], v46 offset:37120
	ds_read_b128 v[210:213], v46 offset:39168
	s_waitcnt lgkmcnt(4)
	v_mfma_f32_16x16x32_bf16 v[142:145], v[178:181], v[194:197], v[142:145]
	s_waitcnt lgkmcnt(2)
	v_mfma_f32_16x16x32_bf16 v[146:149], v[178:181], v[202:205], v[146:149]
	s_waitcnt lgkmcnt(1)
	v_mfma_f32_16x16x32_bf16 v[158:161], v[178:181], v[206:209], v[158:161]
	s_waitcnt lgkmcnt(0)
	v_mfma_f32_16x16x32_bf16 v[22:25], v[178:181], v[210:213], v[22:25]
	v_mfma_f32_16x16x32_bf16 v[26:29], v[198:201], v[194:197], v[26:29]
	v_mfma_f32_16x16x32_bf16 v[30:33], v[198:201], v[202:205], v[30:33]
	v_mfma_f32_16x16x32_bf16 v[66:69], v[198:201], v[206:209], v[66:69]
	v_mfma_f32_16x16x32_bf16 v[54:57], v[198:201], v[210:213], v[54:57]
	ds_read_b128 v[178:181], v45 offset:4352
	ds_read_b128 v[198:201], v45 offset:6400
	s_waitcnt vmcnt(23)
	ds_write_b128 v35, v[90:93] offset:16640
	s_waitcnt vmcnt(21)
	ds_write_b128 v35, v[98:101] offset:20736
	s_waitcnt vmcnt(19)
	ds_write_b128 v35, v[130:133] offset:24832
	s_waitcnt vmcnt(17)
	ds_write_b128 v35, v[138:141] offset:28928
	s_waitcnt lgkmcnt(5)
	v_mfma_f32_16x16x32_bf16 v[182:185], v[178:181], v[194:197], v[182:185]
	v_mfma_f32_16x16x32_bf16 v[186:189], v[178:181], v[202:205], v[186:189]
	v_mfma_f32_16x16x32_bf16 v[190:193], v[178:181], v[206:209], v[190:193]
	v_mfma_f32_16x16x32_bf16 v[70:73], v[178:181], v[210:213], v[70:73]
	s_waitcnt lgkmcnt(4)
	v_mfma_f32_16x16x32_bf16 v[40:43], v[198:201], v[194:197], v[40:43]
	v_mfma_f32_16x16x32_bf16 v[50:53], v[198:201], v[202:205], v[50:53]
	v_mfma_f32_16x16x32_bf16 v[62:65], v[198:201], v[206:209], v[62:65]
	v_mfma_f32_16x16x32_bf16 v[18:21], v[198:201], v[210:213], v[18:21]
	ds_read_b128 v[90:93], v47 offset:256
	ds_read_b128 v[98:101], v48 offset:33024
	ds_read_b128 v[130:133], v47 offset:2304
	ds_read_b128 v[138:141], v48 offset:35072
	ds_read_b128 v[178:181], v48 offset:37120
	ds_read_b128 v[194:197], v48 offset:39168
	s_waitcnt lgkmcnt(4)
	v_mfma_f32_16x16x32_bf16 v[142:145], v[90:93], v[98:101], v[142:145]
	s_waitcnt lgkmcnt(2)
	v_mfma_f32_16x16x32_bf16 v[146:149], v[90:93], v[138:141], v[146:149]
	s_waitcnt lgkmcnt(1)
	v_mfma_f32_16x16x32_bf16 v[158:161], v[90:93], v[178:181], v[158:161]
	s_waitcnt lgkmcnt(0)
	v_mfma_f32_16x16x32_bf16 v[22:25], v[90:93], v[194:197], v[22:25]
	v_mfma_f32_16x16x32_bf16 v[26:29], v[130:133], v[98:101], v[26:29]
	v_mfma_f32_16x16x32_bf16 v[30:33], v[130:133], v[138:141], v[30:33]
	v_mfma_f32_16x16x32_bf16 v[66:69], v[130:133], v[178:181], v[66:69]
	v_mfma_f32_16x16x32_bf16 v[54:57], v[130:133], v[194:197], v[54:57]
	ds_read_b128 v[90:93], v47 offset:4352
	ds_read_b128 v[130:133], v47 offset:6400
	ds_write_b128 v35, v[94:97] offset:49408
	ds_write_b128 v35, v[110:113] offset:53504
	ds_write_b128 v35, v[134:137] offset:57600
	s_waitcnt vmcnt(16)
	ds_write_b128 v35, v[166:169] offset:61696
	s_waitcnt lgkmcnt(5)
	v_mfma_f32_16x16x32_bf16 v[182:185], v[90:93], v[98:101], v[182:185]
	v_mfma_f32_16x16x32_bf16 v[186:189], v[90:93], v[138:141], v[186:189]
	v_mfma_f32_16x16x32_bf16 v[190:193], v[90:93], v[178:181], v[190:193]
	v_mfma_f32_16x16x32_bf16 v[70:73], v[90:93], v[194:197], v[70:73]
	s_waitcnt lgkmcnt(4)
	v_mfma_f32_16x16x32_bf16 v[40:43], v[130:133], v[98:101], v[40:43]
	v_mfma_f32_16x16x32_bf16 v[50:53], v[130:133], v[138:141], v[50:53]
	v_mfma_f32_16x16x32_bf16 v[62:65], v[130:133], v[178:181], v[62:65]
	v_mfma_f32_16x16x32_bf16 v[18:21], v[130:133], v[194:197], v[18:21]
	s_waitcnt lgkmcnt(0)
	s_barrier
	global_load_dwordx4 v[90:93], v[2:3], off offset:1792
	global_load_dwordx4 v[94:97], v[4:5], off offset:1792
	global_load_dwordx4 v[98:101], v[6:7], off offset:1792
	global_load_dwordx4 v[110:113], v[8:9], off offset:1792
	global_load_dwordx4 v[130:133], v[10:11], off offset:1792
	global_load_dwordx4 v[134:137], v[12:13], off offset:1792
	global_load_dwordx4 v[138:141], v[16:17], off offset:1792
	global_load_dwordx4 v[166:169], v[14:15], off offset:1792
	ds_read_b128 v[178:181], v45 offset:16640
	ds_read_b128 v[194:197], v46 offset:49408
	ds_read_b128 v[198:201], v45 offset:18688
	ds_read_b128 v[202:205], v46 offset:51456
	ds_read_b128 v[206:209], v46 offset:53504
	ds_read_b128 v[210:213], v46 offset:55552
	s_waitcnt lgkmcnt(4)
	v_mfma_f32_16x16x32_bf16 v[142:145], v[178:181], v[194:197], v[142:145]
	s_waitcnt lgkmcnt(2)
	v_mfma_f32_16x16x32_bf16 v[146:149], v[178:181], v[202:205], v[146:149]
	s_waitcnt lgkmcnt(1)
	v_mfma_f32_16x16x32_bf16 v[158:161], v[178:181], v[206:209], v[158:161]
	s_waitcnt lgkmcnt(0)
	v_mfma_f32_16x16x32_bf16 v[22:25], v[178:181], v[210:213], v[22:25]
	v_mfma_f32_16x16x32_bf16 v[26:29], v[198:201], v[194:197], v[26:29]
	v_mfma_f32_16x16x32_bf16 v[30:33], v[198:201], v[202:205], v[30:33]
	v_mfma_f32_16x16x32_bf16 v[66:69], v[198:201], v[206:209], v[66:69]
	v_mfma_f32_16x16x32_bf16 v[54:57], v[198:201], v[210:213], v[54:57]
	ds_read_b128 v[178:181], v45 offset:20736
	ds_read_b128 v[198:201], v45 offset:22784
	s_waitcnt vmcnt(23)
	ds_write_b128 v35, v[58:61] offset:256
	s_waitcnt vmcnt(21)
; #define MFMA16(a, b, c) __builtin_amdgcn_mfma_f32_16x16x32_bf16((a), (b), (c), 0, 0, 0)
; DI void gemm_mainloop(const u16* __restrict__ A, const u16* __restrict__ Bt, int tm, int tn, char* smem, f32x4 (&acc)[4][4]) {
;     ...
; #pragma unroll
;   for (int kt = 0; kt < 16; kt++) {
;     const int cur = kt & 1;
;     if (kt + 3 < 16) {
; #pragma unroll
;       for (int i = 0; i < 4; i++) {
;         ra[kt % 3][i] = *(const u32x4*)(Ag + (size_t)(32 * i) * 1024 + (kt + 3) * 64);
;         rb[kt % 3][i] = *(const u32x4*)(Bg + (size_t)(32 * i) * 1024 + (kt + 3) * 64);
;       }
;     }
;     __builtin_amdgcn_sched_barrier(0);
;     const char* Ac = As + cur * 16384; const char* Bc = Bs + cur * 16384;
; #pragma unroll
;     for (int ks = 0; ks < 2; ks++) {
;       bf16x8 af[4], bfr[4];
; #pragma unroll
;       for (int mt = 0; mt < 4; mt++) af[mt] = ldfrag(Ac, gswz(wm * 64 + mt * 16 + l15, ks * 4 + g));
; #pragma unroll
;       for (int nt = 0; nt < 4; nt++) bfr[nt] = ldfrag(Bc, gswz(wn * 64 + nt * 16 + l15, ks * 4 + g));
; #pragma unroll
;       for (int mt = 0; mt < 4; mt++)
; #pragma unroll
;         for (int nt = 0; nt < 4; nt++) acc[mt][nt] = MFMA16(af[mt], bfr[nt], acc[mt][nt]);
;       if (kt + 1 < 16) {
;         char* Xn = (ks == 0 ? As : Bs) + (cur ^ 1) * 16384;
; #pragma unroll
;         for (int i = 0; i < 4; i++) *(u32x4*)(Xn + gswz(lrow + 32 * i, lch)) = (ks == 0 ? ra[(kt + 1) % 3][i] : rb[(kt + 1) % 3][i]);
;       }
;       __builtin_amdgcn_sched_barrier(0);
;     }
;     __syncthreads();
;   }
	ds_write_b128 v35, v[78:81] offset:4352
	s_waitcnt vmcnt(19)
	ds_write_b128 v35, v[114:117] offset:8448
	s_waitcnt vmcnt(17)
	ds_write_b128 v35, v[122:125] offset:12544
	s_waitcnt lgkmcnt(5)
	v_mfma_f32_16x16x32_bf16 v[182:185], v[178:181], v[194:197], v[182:185]
	v_mfma_f32_16x16x32_bf16 v[186:189], v[178:181], v[202:205], v[186:189]
	v_mfma_f32_16x16x32_bf16 v[190:193], v[178:181], v[206:209], v[190:193]
	v_mfma_f32_16x16x32_bf16 v[70:73], v[178:181], v[210:213], v[70:73]
	s_waitcnt lgkmcnt(4)
	v_mfma_f32_16x16x32_bf16 v[40:43], v[198:201], v[194:197], v[40:43]
	v_mfma_f32_16x16x32_bf16 v[50:53], v[198:201], v[202:205], v[50:53]
	v_mfma_f32_16x16x32_bf16 v[62:65], v[198:201], v[206:209], v[62:65]
	v_mfma_f32_16x16x32_bf16 v[18:21], v[198:201], v[210:213], v[18:21]
	ds_read_b128 v[58:61], v47 offset:16640
	ds_read_b128 v[78:81], v48 offset:49408
	ds_read_b128 v[114:117], v47 offset:18688
	ds_read_b128 v[122:125], v48 offset:51456
	ds_read_b128 v[178:181], v48 offset:53504
	ds_read_b128 v[194:197], v48 offset:55552
	s_waitcnt lgkmcnt(4)
	v_mfma_f32_16x16x32_bf16 v[142:145], v[58:61], v[78:81], v[142:145]
	s_waitcnt lgkmcnt(2)
	v_mfma_f32_16x16x32_bf16 v[146:149], v[58:61], v[122:125], v[146:149]
	s_waitcnt lgkmcnt(1)
	v_mfma_f32_16x16x32_bf16 v[158:161], v[58:61], v[178:181], v[158:161]
	s_waitcnt lgkmcnt(0)
	v_mfma_f32_16x16x32_bf16 v[22:25], v[58:61], v[194:197], v[22:25]
	v_mfma_f32_16x16x32_bf16 v[26:29], v[114:117], v[78:81], v[26:29]
	v_mfma_f32_16x16x32_bf16 v[30:33], v[114:117], v[122:125], v[30:33]
	v_mfma_f32_16x16x32_bf16 v[58:61], v[114:117], v[178:181], v[66:69]
	v_mfma_f32_16x16x32_bf16 v[54:57], v[114:117], v[194:197], v[54:57]
	s_nop 1
	ds_read_b128 v[66:69], v47 offset:20736
	ds_read_b128 v[114:117], v47 offset:22784
	ds_write_b128 v35, v[74:77] offset:33024
	ds_write_b128 v35, v[102:105] offset:37120
	ds_write_b128 v35, v[118:121] offset:41216
	s_waitcnt vmcnt(16)
	ds_write_b128 v35, v[162:165] offset:45312
	s_waitcnt lgkmcnt(5)
	v_mfma_f32_16x16x32_bf16 v[182:185], v[66:69], v[78:81], v[182:185]
	v_mfma_f32_16x16x32_bf16 v[186:189], v[66:69], v[122:125], v[186:189]
	v_mfma_f32_16x16x32_bf16 v[190:193], v[66:69], v[178:181], v[190:193]
	v_mfma_f32_16x16x32_bf16 v[66:69], v[66:69], v[194:197], v[70:73]
	s_waitcnt lgkmcnt(4)
	v_mfma_f32_16x16x32_bf16 v[40:43], v[114:117], v[78:81], v[40:43]
	v_mfma_f32_16x16x32_bf16 v[50:53], v[114:117], v[122:125], v[50:53]
	v_mfma_f32_16x16x32_bf16 v[62:65], v[114:117], v[178:181], v[62:65]
	v_mfma_f32_16x16x32_bf16 v[18:21], v[114:117], v[194:197], v[18:21]
	s_waitcnt lgkmcnt(0)
	s_barrier
	global_load_dwordx4 v[70:73], v[2:3], off offset:1920
	s_nop 0
	global_load_dwordx4 v[2:5], v[4:5], off offset:1920
	s_nop 0
	global_load_dwordx4 v[74:77], v[6:7], off offset:1920
	s_nop 0
	global_load_dwordx4 v[6:9], v[8:9], off offset:1920
	s_nop 0
	global_load_dwordx4 v[78:81], v[10:11], off offset:1920
	s_nop 0
	global_load_dwordx4 v[10:13], v[12:13], off offset:1920
	s_nop 0
	global_load_dwordx4 v[102:105], v[16:17], off offset:1920
	s_nop 0
	global_load_dwordx4 v[14:17], v[14:15], off offset:1920
	ds_read_b128 v[114:117], v45 offset:256
	ds_read_b128 v[118:121], v46 offset:33024
	ds_read_b128 v[122:125], v45 offset:2304
	ds_read_b128 v[162:165], v46 offset:35072
	ds_read_b128 v[178:181], v46 offset:37120
	ds_read_b128 v[194:197], v46 offset:39168
	s_waitcnt lgkmcnt(4)
	v_mfma_f32_16x16x32_bf16 v[142:145], v[114:117], v[118:121], v[142:145]
	s_waitcnt lgkmcnt(2)
	v_mfma_f32_16x16x32_bf16 v[146:149], v[114:117], v[162:165], v[146:149]
	s_waitcnt lgkmcnt(1)
	v_mfma_f32_16x16x32_bf16 v[158:161], v[114:117], v[178:181], v[158:161]
	s_waitcnt lgkmcnt(0)
	v_mfma_f32_16x16x32_bf16 v[22:25], v[114:117], v[194:197], v[22:25]
	v_mfma_f32_16x16x32_bf16 v[26:29], v[122:125], v[118:121], v[26:29]
	v_mfma_f32_16x16x32_bf16 v[30:33], v[122:125], v[162:165], v[30:33]
	v_mfma_f32_16x16x32_bf16 v[58:61], v[122:125], v[178:181], v[58:61]
	v_mfma_f32_16x16x32_bf16 v[54:57], v[122:125], v[194:197], v[54:57]
	ds_read_b128 v[114:117], v45 offset:4352
	ds_read_b128 v[122:125], v45 offset:6400
	s_waitcnt vmcnt(23)
	ds_write_b128 v35, v[82:85] offset:16640
	s_waitcnt vmcnt(21)
	ds_write_b128 v35, v[106:109] offset:20736
	s_waitcnt vmcnt(19)
	ds_write_b128 v35, v[150:153] offset:24832
	s_waitcnt vmcnt(17)
	ds_write_b128 v35, v[170:173] offset:28928
	s_waitcnt lgkmcnt(5)
	v_mfma_f32_16x16x32_bf16 v[182:185], v[114:117], v[118:121], v[182:185]
	v_mfma_f32_16x16x32_bf16 v[186:189], v[114:117], v[162:165], v[186:189]
	v_mfma_f32_16x16x32_bf16 v[190:193], v[114:117], v[178:181], v[190:193]
	v_mfma_f32_16x16x32_bf16 v[66:69], v[114:117], v[194:197], v[66:69]
	s_waitcnt lgkmcnt(4)
	v_mfma_f32_16x16x32_bf16 v[40:43], v[122:125], v[118:121], v[40:43]
	v_mfma_f32_16x16x32_bf16 v[50:53], v[122:125], v[162:165], v[50:53]
	v_mfma_f32_16x16x32_bf16 v[62:65], v[122:125], v[178:181], v[62:65]
	v_mfma_f32_16x16x32_bf16 v[18:21], v[122:125], v[194:197], v[18:21]
	ds_read_b128 v[82:85], v47 offset:256
	ds_read_b128 v[106:109], v48 offset:33024
	ds_read_b128 v[114:117], v47 offset:2304
	ds_read_b128 v[118:121], v48 offset:35072
	s_waitcnt lgkmcnt(2)
	v_mfma_f32_16x16x32_bf16 v[122:125], v[82:85], v[106:109], v[142:145]
	s_waitcnt lgkmcnt(0)
	v_mfma_f32_16x16x32_bf16 v[142:145], v[82:85], v[118:121], v[146:149]
	s_nop 2
	ds_read_b128 v[146:149], v48 offset:37120
	ds_read_b128 v[150:153], v48 offset:39168
	s_waitcnt lgkmcnt(1)
	v_mfma_f32_16x16x32_bf16 v[158:161], v[82:85], v[146:149], v[158:161]
	s_waitcnt lgkmcnt(0)
	v_mfma_f32_16x16x32_bf16 v[22:25], v[82:85], v[150:153], v[22:25]
	v_mfma_f32_16x16x32_bf16 v[26:29], v[114:117], v[106:109], v[26:29]
	v_mfma_f32_16x16x32_bf16 v[30:33], v[114:117], v[118:121], v[30:33]
	v_mfma_f32_16x16x32_bf16 v[58:61], v[114:117], v[146:149], v[58:61]
	v_mfma_f32_16x16x32_bf16 v[54:57], v[114:117], v[150:153], v[54:57]
	ds_read_b128 v[82:85], v47 offset:4352
	ds_read_b128 v[114:117], v47 offset:6400
	ds_write_b128 v35, v[86:89] offset:49408
	ds_write_b128 v35, v[126:129] offset:53504
	ds_write_b128 v35, v[154:157] offset:57600
	s_waitcnt vmcnt(16)
	ds_write_b128 v35, v[174:177] offset:61696
	s_waitcnt lgkmcnt(5)
	v_mfma_f32_16x16x32_bf16 v[162:165], v[82:85], v[106:109], v[182:185]
	v_mfma_f32_16x16x32_bf16 v[170:173], v[82:85], v[118:121], v[186:189]
	v_mfma_f32_16x16x32_bf16 v[178:181], v[82:85], v[146:149], v[190:193]
	v_mfma_f32_16x16x32_bf16 v[66:69], v[82:85], v[150:153], v[66:69]
	s_waitcnt lgkmcnt(4)
	v_mfma_f32_16x16x32_bf16 v[40:43], v[114:117], v[106:109], v[40:43]
	v_mfma_f32_16x16x32_bf16 v[50:53], v[114:117], v[118:121], v[50:53]
	v_mfma_f32_16x16x32_bf16 v[62:65], v[114:117], v[146:149], v[62:65]
	v_mfma_f32_16x16x32_bf16 v[18:21], v[114:117], v[150:153], v[18:21]
	s_waitcnt lgkmcnt(0)
	s_barrier
; #define MFMA16(a, b, c) __builtin_amdgcn_mfma_f32_16x16x32_bf16((a), (b), (c), 0, 0, 0)
; DI void gemm_mainloop(const u16* __restrict__ A, const u16* __restrict__ Bt, int tm, int tn, char* smem, f32x4 (&acc)[4][4]) {
;     ...
; #pragma unroll
;   for (int kt = 0; kt < 16; kt++) {
;     const int cur = kt & 1;
;     if (kt + 3 < 16) {
; #pragma unroll
;       for (int i = 0; i < 4; i++) {
;         ra[kt % 3][i] = *(const u32x4*)(Ag + (size_t)(32 * i) * 1024 + (kt + 3) * 64);
;         rb[kt % 3][i] = *(const u32x4*)(Bg + (size_t)(32 * i) * 1024 + (kt + 3) * 64);
;       }
;     }
;     __builtin_amdgcn_sched_barrier(0);
;     const char* Ac = As + cur * 16384; const char* Bc = Bs + cur * 16384;
; #pragma unroll
;     for (int ks = 0; ks < 2; ks++) {
;       bf16x8 af[4], bfr[4];
; #pragma unroll
;       for (int mt = 0; mt < 4; mt++) af[mt] = ldfrag(Ac, gswz(wm * 64 + mt * 16 + l15, ks * 4 + g));
; #pragma unroll
;       for (int nt = 0; nt < 4; nt++) bfr[nt] = ldfrag(Bc, gswz(wn * 64 + nt * 16 + l15, ks * 4 + g));
; #pragma unroll
;       for (int mt = 0; mt < 4; mt++)
; #pragma unroll
;         for (int nt = 0; nt < 4; nt++) acc[mt][nt] = MFMA16(af[mt], bfr[nt], acc[mt][nt]);
;       if (kt + 1 < 16) {
;         char* Xn = (ks == 0 ? As : Bs) + (cur ^ 1) * 16384;
; #pragma unroll
;         for (int i = 0; i < 4; i++) *(u32x4*)(Xn + gswz(lrow + 32 * i, lch)) = (ks == 0 ? ra[(kt + 1) % 3][i] : rb[(kt + 1) % 3][i]);
;       }
;       __builtin_amdgcn_sched_barrier(0);
;     }
;     __syncthreads();
;   }
	ds_read_b128 v[82:85], v45 offset:16640
	ds_read_b128 v[86:89], v46 offset:49408
	ds_read_b128 v[106:109], v45 offset:18688
	ds_read_b128 v[114:117], v46 offset:51456
	s_waitcnt lgkmcnt(2)
	v_mfma_f32_16x16x32_bf16 v[118:121], v[82:85], v[86:89], v[122:125]
	s_waitcnt lgkmcnt(0)
	v_mfma_f32_16x16x32_bf16 v[122:125], v[82:85], v[114:117], v[142:145]
	ds_read_b128 v[126:129], v46 offset:53504
	s_nop 1
	ds_read_b128 v[142:145], v46 offset:55552
	s_waitcnt lgkmcnt(1)
	v_mfma_f32_16x16x32_bf16 v[146:149], v[82:85], v[126:129], v[158:161]
	s_waitcnt lgkmcnt(0)
	v_mfma_f32_16x16x32_bf16 v[22:25], v[82:85], v[142:145], v[22:25]
	v_mfma_f32_16x16x32_bf16 v[26:29], v[106:109], v[86:89], v[26:29]
	v_mfma_f32_16x16x32_bf16 v[30:33], v[106:109], v[114:117], v[30:33]
	v_mfma_f32_16x16x32_bf16 v[58:61], v[106:109], v[126:129], v[58:61]
	v_mfma_f32_16x16x32_bf16 v[54:57], v[106:109], v[142:145], v[54:57]
	ds_read_b128 v[82:85], v45 offset:20736
	ds_read_b128 v[106:109], v45 offset:22784
	s_waitcnt vmcnt(15)
	ds_write_b128 v35, v[90:93] offset:256
	s_waitcnt vmcnt(13)
	ds_write_b128 v35, v[98:101] offset:4352
	s_waitcnt vmcnt(11)
	ds_write_b128 v35, v[130:133] offset:8448
	s_waitcnt vmcnt(9)
	ds_write_b128 v35, v[138:141] offset:12544
	s_waitcnt lgkmcnt(5)
	v_mfma_f32_16x16x32_bf16 v[150:153], v[82:85], v[86:89], v[162:165]
	v_mfma_f32_16x16x32_bf16 v[154:157], v[82:85], v[114:117], v[170:173]
	v_mfma_f32_16x16x32_bf16 v[158:161], v[82:85], v[126:129], v[178:181]
	v_mfma_f32_16x16x32_bf16 v[66:69], v[82:85], v[142:145], v[66:69]
	s_waitcnt lgkmcnt(4)
	v_mfma_f32_16x16x32_bf16 v[40:43], v[106:109], v[86:89], v[40:43]
	v_mfma_f32_16x16x32_bf16 v[50:53], v[106:109], v[114:117], v[50:53]
	v_mfma_f32_16x16x32_bf16 v[62:65], v[106:109], v[126:129], v[62:65]
	v_mfma_f32_16x16x32_bf16 v[18:21], v[106:109], v[142:145], v[18:21]
	ds_read_b128 v[82:85], v47 offset:16640
	ds_read_b128 v[86:89], v48 offset:49408
	ds_read_b128 v[90:93], v47 offset:18688
	ds_read_b128 v[98:101], v48 offset:51456
	s_waitcnt lgkmcnt(2)
	v_mfma_f32_16x16x32_bf16 v[106:109], v[82:85], v[86:89], v[118:121]
	s_waitcnt lgkmcnt(0)
	v_mfma_f32_16x16x32_bf16 v[114:117], v[82:85], v[98:101], v[122:125]
	s_nop 0
	ds_read_b128 v[118:121], v48 offset:53504
	s_nop 0
	ds_read_b128 v[122:125], v48 offset:55552
	s_waitcnt lgkmcnt(1)
	v_mfma_f32_16x16x32_bf16 v[126:129], v[82:85], v[118:121], v[146:149]
	s_waitcnt lgkmcnt(0)
	v_mfma_f32_16x16x32_bf16 v[22:25], v[82:85], v[122:125], v[22:25]
	v_mfma_f32_16x16x32_bf16 v[26:29], v[90:93], v[86:89], v[26:29]
	v_mfma_f32_16x16x32_bf16 v[30:33], v[90:93], v[98:101], v[30:33]
	v_mfma_f32_16x16x32_bf16 v[58:61], v[90:93], v[118:121], v[58:61]
	v_mfma_f32_16x16x32_bf16 v[54:57], v[90:93], v[122:125], v[54:57]
	ds_read_b128 v[82:85], v47 offset:20736
	ds_read_b128 v[90:93], v47 offset:22784
	ds_write_b128 v35, v[94:97] offset:33024
	ds_write_b128 v35, v[110:113] offset:37120
	ds_write_b128 v35, v[134:137] offset:41216
	s_waitcnt vmcnt(8)
	ds_write_b128 v35, v[166:169] offset:45312
	s_waitcnt lgkmcnt(5)
	v_mfma_f32_16x16x32_bf16 v[130:133], v[82:85], v[86:89], v[150:153]
	v_mfma_f32_16x16x32_bf16 v[138:141], v[82:85], v[98:101], v[154:157]
	v_mfma_f32_16x16x32_bf16 v[142:145], v[82:85], v[118:121], v[158:161]
	v_mfma_f32_16x16x32_bf16 v[66:69], v[82:85], v[122:125], v[66:69]
	s_waitcnt lgkmcnt(4)
	v_mfma_f32_16x16x32_bf16 v[40:43], v[90:93], v[86:89], v[40:43]
	v_mfma_f32_16x16x32_bf16 v[50:53], v[90:93], v[98:101], v[50:53]
	v_mfma_f32_16x16x32_bf16 v[62:65], v[90:93], v[118:121], v[62:65]
	v_mfma_f32_16x16x32_bf16 v[18:21], v[90:93], v[122:125], v[18:21]
	s_waitcnt lgkmcnt(0)
	s_barrier
	ds_read_b128 v[82:85], v45 offset:256
	ds_read_b128 v[86:89], v46 offset:33024
	ds_read_b128 v[90:93], v45 offset:2304
	ds_read_b128 v[94:97], v46 offset:35072
	s_waitcnt lgkmcnt(2)
	v_mfma_f32_16x16x32_bf16 v[98:101], v[82:85], v[86:89], v[106:109]
	s_waitcnt lgkmcnt(0)
	v_mfma_f32_16x16x32_bf16 v[106:109], v[82:85], v[94:97], v[114:117]
	ds_read_b128 v[110:113], v46 offset:37120
	s_nop 1
	ds_read_b128 v[114:117], v46 offset:39168
	s_waitcnt lgkmcnt(1)
	v_mfma_f32_16x16x32_bf16 v[118:121], v[82:85], v[110:113], v[126:129]
	s_waitcnt lgkmcnt(0)
	v_mfma_f32_16x16x32_bf16 v[22:25], v[82:85], v[114:117], v[22:25]
	v_mfma_f32_16x16x32_bf16 v[26:29], v[90:93], v[86:89], v[26:29]
	v_mfma_f32_16x16x32_bf16 v[30:33], v[90:93], v[94:97], v[30:33]
	v_mfma_f32_16x16x32_bf16 v[58:61], v[90:93], v[110:113], v[58:61]
	v_mfma_f32_16x16x32_bf16 v[54:57], v[90:93], v[114:117], v[54:57]
	ds_read_b128 v[82:85], v45 offset:4352
	ds_read_b128 v[90:93], v45 offset:6400
	s_waitcnt vmcnt(7)
	ds_write_b128 v35, v[70:73] offset:16640
	s_waitcnt vmcnt(5)
	ds_write_b128 v35, v[74:77] offset:20736
	s_waitcnt vmcnt(3)
	ds_write_b128 v35, v[78:81] offset:24832
	s_waitcnt vmcnt(1)
	ds_write_b128 v35, v[102:105] offset:28928
	s_waitcnt lgkmcnt(5)
	v_mfma_f32_16x16x32_bf16 v[122:125], v[82:85], v[86:89], v[130:133]
	v_mfma_f32_16x16x32_bf16 v[126:129], v[82:85], v[94:97], v[138:141]
	v_mfma_f32_16x16x32_bf16 v[130:133], v[82:85], v[110:113], v[142:145]
	v_mfma_f32_16x16x32_bf16 v[66:69], v[82:85], v[114:117], v[66:69]
	s_waitcnt lgkmcnt(4)
	v_mfma_f32_16x16x32_bf16 v[40:43], v[90:93], v[86:89], v[40:43]
	v_mfma_f32_16x16x32_bf16 v[50:53], v[90:93], v[94:97], v[50:53]
	v_mfma_f32_16x16x32_bf16 v[62:65], v[90:93], v[110:113], v[62:65]
	v_mfma_f32_16x16x32_bf16 v[18:21], v[90:93], v[114:117], v[18:21]
	ds_read_b128 v[70:73], v47 offset:256
	ds_read_b128 v[74:77], v48 offset:33024
	ds_read_b128 v[78:81], v47 offset:2304
	ds_read_b128 v[82:85], v48 offset:35072
	s_waitcnt lgkmcnt(2)
; #define MFMA16(a, b, c) __builtin_amdgcn_mfma_f32_16x16x32_bf16((a), (b), (c), 0, 0, 0)
; DI void gemm_mainloop(const u16* __restrict__ A, const u16* __restrict__ Bt, int tm, int tn, char* smem, f32x4 (&acc)[4][4]) {
;     ...
; #pragma unroll
;     for (int ks = 0; ks < 2; ks++) {
;       bf16x8 af[4], bfr[4];
; #pragma unroll
;       for (int mt = 0; mt < 4; mt++) af[mt] = ldfrag(Ac, gswz(wm * 64 + mt * 16 + l15, ks * 4 + g));
; #pragma unroll
;       for (int nt = 0; nt < 4; nt++) bfr[nt] = ldfrag(Bc, gswz(wn * 64 + nt * 16 + l15, ks * 4 + g));
; #pragma unroll
;       for (int mt = 0; mt < 4; mt++)
; #pragma unroll
;         for (int nt = 0; nt < 4; nt++) acc[mt][nt] = MFMA16(af[mt], bfr[nt], acc[mt][nt]);
;       if (kt + 1 < 16) {
;         char* Xn = (ks == 0 ? As : Bs) + (cur ^ 1) * 16384;
; #pragma unroll
;         for (int i = 0; i < 4; i++) *(u32x4*)(Xn + gswz(lrow + 32 * i, lch)) = (ks == 0 ? ra[(kt + 1) % 3][i] : rb[(kt + 1) % 3][i]);
;       }
;       __builtin_amdgcn_sched_barrier(0);
;     }
;     __syncthreads();
;   }
; DI void phase_gemm_out(const Params& p, int bid, int nb, char* smem) {
;     ...
; #pragma unroll
;     for (int mt = 0; mt < 4; mt++)
; #pragma unroll
;       for (int r4 = 0; r4 < 4; r4++) {
;         const int row = tm * 128 + wm * 64 + mt * 16 + g * 4 + r4;
; #pragma unroll
;         for (int nt = 0; nt < 4; nt++) {
;           const size_t idx = (size_t)row * 1024 + tn * 128 + wn * 64 + nt * 16 + l15;
;           p.out[idx] = p.x[idx] + acc[mt][nt][r4];
	v_mfma_f32_16x16x32_bf16 v[86:89], v[70:73], v[74:77], v[98:101]
	ds_read_b128 v[94:97], v48 offset:37120
	s_nop 1
	ds_read_b128 v[98:101], v48 offset:39168
	s_waitcnt lgkmcnt(2)
	v_mfma_f32_16x16x32_bf16 v[90:93], v[70:73], v[82:85], v[106:109]
	s_waitcnt lgkmcnt(1)
	v_mfma_f32_16x16x32_bf16 v[102:105], v[70:73], v[94:97], v[118:121]
	s_waitcnt lgkmcnt(0)
	v_mfma_f32_16x16x32_bf16 v[22:25], v[70:73], v[98:101], v[22:25]
	v_mfma_f32_16x16x32_bf16 v[26:29], v[78:81], v[74:77], v[26:29]
	v_mfma_f32_16x16x32_bf16 v[30:33], v[78:81], v[82:85], v[30:33]
	v_mfma_f32_16x16x32_bf16 v[58:61], v[78:81], v[94:97], v[58:61]
	v_mfma_f32_16x16x32_bf16 v[54:57], v[78:81], v[98:101], v[54:57]
	ds_read_b128 v[70:73], v47 offset:4352
	ds_read_b128 v[78:81], v47 offset:6400
	ds_write_b128 v35, v[2:5] offset:49408
	ds_write_b128 v35, v[6:9] offset:53504
	ds_write_b128 v35, v[10:13] offset:57600
	s_waitcnt vmcnt(0)
	ds_write_b128 v35, v[14:17] offset:61696
	s_waitcnt lgkmcnt(5)
	v_mfma_f32_16x16x32_bf16 v[106:109], v[70:73], v[74:77], v[122:125]
	v_mfma_f32_16x16x32_bf16 v[110:113], v[70:73], v[82:85], v[126:129]
	v_mfma_f32_16x16x32_bf16 v[114:117], v[70:73], v[94:97], v[130:133]
	v_mfma_f32_16x16x32_bf16 v[66:69], v[70:73], v[98:101], v[66:69]
	s_waitcnt lgkmcnt(4)
	v_mfma_f32_16x16x32_bf16 v[40:43], v[78:81], v[74:77], v[40:43]
	v_mfma_f32_16x16x32_bf16 v[50:53], v[78:81], v[82:85], v[50:53]
	v_mfma_f32_16x16x32_bf16 v[62:65], v[78:81], v[94:97], v[62:65]
	v_mfma_f32_16x16x32_bf16 v[2:5], v[78:81], v[98:101], v[18:21]
	s_waitcnt lgkmcnt(0)
	s_barrier
	ds_read_b128 v[6:9], v45 offset:16640
	ds_read_b128 v[10:13], v46 offset:49408
	ds_read_b128 v[14:17], v45 offset:18688
	ds_read_b128 v[18:21], v46 offset:51456
	ds_read_b128 v[78:81], v46 offset:53504
	ds_read_b128 v[82:85], v46 offset:55552
	s_waitcnt lgkmcnt(4)
	v_mfma_f32_16x16x32_bf16 v[70:73], v[6:9], v[10:13], v[86:89]
	s_waitcnt lgkmcnt(2)
	v_mfma_f32_16x16x32_bf16 v[74:77], v[6:9], v[18:21], v[90:93]
	s_waitcnt lgkmcnt(1)
	v_mfma_f32_16x16x32_bf16 v[86:89], v[6:9], v[78:81], v[102:105]
	s_waitcnt lgkmcnt(0)
	v_mfma_f32_16x16x32_bf16 v[6:9], v[6:9], v[82:85], v[22:25]
	v_mfma_f32_16x16x32_bf16 v[22:25], v[14:17], v[10:13], v[26:29]
	v_mfma_f32_16x16x32_bf16 v[26:29], v[14:17], v[18:21], v[30:33]
	v_mfma_f32_16x16x32_bf16 v[30:33], v[14:17], v[78:81], v[58:61]
	v_mfma_f32_16x16x32_bf16 v[14:17], v[14:17], v[82:85], v[54:57]
	s_nop 2
	ds_read_b128 v[54:57], v45 offset:20736
	ds_read_b128 v[58:61], v45 offset:22784
	s_waitcnt lgkmcnt(1)
	v_mfma_f32_16x16x32_bf16 v[90:93], v[54:57], v[10:13], v[106:109]
	v_mfma_f32_16x16x32_bf16 v[94:97], v[54:57], v[18:21], v[110:113]
	v_mfma_f32_16x16x32_bf16 v[98:101], v[54:57], v[78:81], v[114:117]
	v_mfma_f32_16x16x32_bf16 v[54:57], v[54:57], v[82:85], v[66:69]
	s_waitcnt lgkmcnt(0)
	v_mfma_f32_16x16x32_bf16 v[10:13], v[58:61], v[10:13], v[40:43]
	v_mfma_f32_16x16x32_bf16 v[40:43], v[58:61], v[18:21], v[50:53]
	v_mfma_f32_16x16x32_bf16 v[50:53], v[58:61], v[78:81], v[62:65]
	v_mfma_f32_16x16x32_bf16 v[2:5], v[58:61], v[82:85], v[2:5]
	ds_read_b128 v[18:21], v47 offset:16640
	ds_read_b128 v[58:61], v48 offset:49408
	ds_read_b128 v[62:65], v47 offset:18688
	ds_read_b128 v[66:69], v48 offset:51456
	ds_read_b128 v[78:81], v48 offset:53504
	ds_read_b128 v[82:85], v48 offset:55552
	s_waitcnt lgkmcnt(4)
	v_mfma_f32_16x16x32_bf16 v[70:73], v[18:21], v[58:61], v[70:73]
	s_waitcnt lgkmcnt(0)
	v_mfma_f32_16x16x32_bf16 v[102:105], v[18:21], v[82:85], v[6:9]
	s_nop 2
	ds_read_b128 v[6:9], v47 offset:20736
	ds_read_b128 v[118:121], v47 offset:22784
	v_mfma_f32_16x16x32_bf16 v[74:77], v[18:21], v[66:69], v[74:77]
	v_mfma_f32_16x16x32_bf16 v[86:89], v[18:21], v[78:81], v[86:89]
	v_mfma_f32_16x16x32_bf16 v[106:109], v[62:65], v[58:61], v[22:25]
	v_mfma_f32_16x16x32_bf16 v[110:113], v[62:65], v[66:69], v[26:29]
	v_mfma_f32_16x16x32_bf16 v[114:117], v[62:65], v[78:81], v[30:33]
	v_mfma_f32_16x16x32_bf16 v[62:65], v[62:65], v[82:85], v[14:17]
	s_waitcnt lgkmcnt(1)
	v_mfma_f32_16x16x32_bf16 v[30:33], v[6:9], v[58:61], v[90:93]
	v_mfma_f32_16x16x32_bf16 v[26:29], v[6:9], v[66:69], v[94:97]
	v_mfma_f32_16x16x32_bf16 v[22:25], v[6:9], v[78:81], v[98:101]
	v_mfma_f32_16x16x32_bf16 v[18:21], v[6:9], v[82:85], v[54:57]
	s_waitcnt lgkmcnt(0)
	v_mfma_f32_16x16x32_bf16 v[14:17], v[118:121], v[58:61], v[10:13]
	v_mfma_f32_16x16x32_bf16 v[10:13], v[118:121], v[66:69], v[40:43]
	v_mfma_f32_16x16x32_bf16 v[6:9], v[118:121], v[78:81], v[50:53]
	v_mfma_f32_16x16x32_bf16 v[2:5], v[118:121], v[82:85], v[2:5]
	s_nop 0
	v_or_b32_e32 v42, s9, v44
	s_ashr_i32 s9, s10, 31
	v_ashrrev_i32_e32 v43, 31, v42
	v_mov_b32_e32 v41, s9
	v_or_b32_e32 v40, s10, v34
	v_lshlrev_b64 v[50:51], 10, v[42:43]
	v_lshl_add_u64 v[50:51], v[50:51], 0, v[40:41]
	v_lshlrev_b64 v[50:51], 2, v[50:51]
	v_lshl_add_u64 v[194:195], s[12:13], 0, v[50:51]
	v_lshl_add_u64 v[196:197], s[42:43], 0, v[50:51]
	s_barrier
; DI void phase_gemm_out(const Params& p, int bid, int nb, char* smem) {
;     ...
; #pragma unroll
;     for (int mt = 0; mt < 4; mt++)
; #pragma unroll
;       for (int r4 = 0; r4 < 4; r4++) {
;         const int row = tm * 128 + wm * 64 + mt * 16 + g * 4 + r4;
; #pragma unroll
;         for (int nt = 0; nt < 4; nt++) {
;           const size_t idx = (size_t)row * 1024 + tn * 128 + wn * 64 + nt * 16 + l15;
;           p.out[idx] = p.x[idx] + acc[mt][nt][r4];
	s_add_i32 s4, s4, 1
	s_mul_i32 s9, s4, s1
	s_add_i32 s8, s8, s1
	s_add_i32 s9, s9, s0
	s_mov_b64 s[98:99], 0x1000
	global_load_dword v130, v[194:195], off
	global_load_dword v131, v[194:195], off offset:64
	global_load_dword v132, v[194:195], off offset:128
	global_load_dword v133, v[194:195], off offset:192
	v_lshl_add_u64 v[194:195], v[194:195], 0, s[98:99]
	global_load_dword v134, v[194:195], off
	global_load_dword v135, v[194:195], off offset:64
	global_load_dword v136, v[194:195], off offset:128
	global_load_dword v137, v[194:195], off offset:192
	v_lshl_add_u64 v[194:195], v[194:195], 0, s[98:99]
	global_load_dword v138, v[194:195], off
	global_load_dword v139, v[194:195], off offset:64
	global_load_dword v140, v[194:195], off offset:128
	global_load_dword v141, v[194:195], off offset:192
	v_lshl_add_u64 v[194:195], v[194:195], 0, s[98:99]
	global_load_dword v142, v[194:195], off
	global_load_dword v143, v[194:195], off offset:64
	global_load_dword v144, v[194:195], off offset:128
	global_load_dword v145, v[194:195], off offset:192
	s_mov_b64 s[98:99], 0xd000
	v_lshl_add_u64 v[194:195], v[194:195], 0, s[98:99]
	s_mov_b64 s[98:99], 0x1000
	global_load_dword v146, v[194:195], off
	global_load_dword v147, v[194:195], off offset:64
	global_load_dword v148, v[194:195], off offset:128
	global_load_dword v149, v[194:195], off offset:192
	v_lshl_add_u64 v[194:195], v[194:195], 0, s[98:99]
	global_load_dword v150, v[194:195], off
	global_load_dword v151, v[194:195], off offset:64
	global_load_dword v152, v[194:195], off offset:128
	global_load_dword v153, v[194:195], off offset:192
	v_lshl_add_u64 v[194:195], v[194:195], 0, s[98:99]
	global_load_dword v154, v[194:195], off
	global_load_dword v155, v[194:195], off offset:64
	global_load_dword v156, v[194:195], off offset:128
	global_load_dword v157, v[194:195], off offset:192
	v_lshl_add_u64 v[194:195], v[194:195], 0, s[98:99]
	global_load_dword v158, v[194:195], off
	global_load_dword v159, v[194:195], off offset:64
	global_load_dword v160, v[194:195], off offset:128
	global_load_dword v161, v[194:195], off offset:192
	s_mov_b64 s[98:99], 0xd000
	v_lshl_add_u64 v[194:195], v[194:195], 0, s[98:99]
	s_mov_b64 s[98:99], 0x1000
	global_load_dword v162, v[194:195], off
	global_load_dword v163, v[194:195], off offset:64
	global_load_dword v164, v[194:195], off offset:128
	global_load_dword v165, v[194:195], off offset:192
	v_lshl_add_u64 v[194:195], v[194:195], 0, s[98:99]
	global_load_dword v166, v[194:195], off
	global_load_dword v167, v[194:195], off offset:64
	global_load_dword v168, v[194:195], off offset:128
	global_load_dword v169, v[194:195], off offset:192
	v_lshl_add_u64 v[194:195], v[194:195], 0, s[98:99]
	global_load_dword v170, v[194:195], off
	global_load_dword v171, v[194:195], off offset:64
	global_load_dword v172, v[194:195], off offset:128
	global_load_dword v173, v[194:195], off offset:192
	v_lshl_add_u64 v[194:195], v[194:195], 0, s[98:99]
	global_load_dword v174, v[194:195], off
	global_load_dword v175, v[194:195], off offset:64
	global_load_dword v176, v[194:195], off offset:128
	global_load_dword v177, v[194:195], off offset:192
	s_mov_b64 s[98:99], 0xd000
	v_lshl_add_u64 v[194:195], v[194:195], 0, s[98:99]
	s_mov_b64 s[98:99], 0x1000
	global_load_dword v178, v[194:195], off
	global_load_dword v179, v[194:195], off offset:64
	global_load_dword v180, v[194:195], off offset:128
	global_load_dword v181, v[194:195], off offset:192
	v_lshl_add_u64 v[194:195], v[194:195], 0, s[98:99]
	global_load_dword v182, v[194:195], off
	global_load_dword v183, v[194:195], off offset:64
	global_load_dword v184, v[194:195], off offset:128
	global_load_dword v185, v[194:195], off offset:192
	v_lshl_add_u64 v[194:195], v[194:195], 0, s[98:99]
	global_load_dword v186, v[194:195], off
	global_load_dword v187, v[194:195], off offset:64
	global_load_dword v188, v[194:195], off offset:128
	global_load_dword v189, v[194:195], off offset:192
	v_lshl_add_u64 v[194:195], v[194:195], 0, s[98:99]
	global_load_dword v190, v[194:195], off
	global_load_dword v191, v[194:195], off offset:64
	global_load_dword v192, v[194:195], off offset:128
	global_load_dword v193, v[194:195], off offset:192
	s_mov_b64 s[98:99], 0x1000
	s_waitcnt vmcnt(60)
	v_add_f32_e32 v130, v70, v130
	v_add_f32_e32 v131, v74, v131
	v_add_f32_e32 v132, v86, v132
	v_add_f32_e32 v133, v102, v133
	global_store_dword v[196:197], v130, off
	global_store_dword v[196:197], v131, off offset:64
	global_store_dword v[196:197], v132, off offset:128
	global_store_dword v[196:197], v133, off offset:192
	v_lshl_add_u64 v[196:197], v[196:197], 0, s[98:99]
	s_waitcnt vmcnt(60)
	v_add_f32_e32 v134, v71, v134
	v_add_f32_e32 v135, v75, v135
	v_add_f32_e32 v136, v87, v136
	v_add_f32_e32 v137, v103, v137
	global_store_dword v[196:197], v134, off
	global_store_dword v[196:197], v135, off offset:64
	global_store_dword v[196:197], v136, off offset:128
	global_store_dword v[196:197], v137, off offset:192
	v_lshl_add_u64 v[196:197], v[196:197], 0, s[98:99]
	s_waitcnt vmcnt(60)
	v_add_f32_e32 v138, v72, v138
	v_add_f32_e32 v139, v76, v139
	v_add_f32_e32 v140, v88, v140
	v_add_f32_e32 v141, v104, v141
	global_store_dword v[196:197], v138, off
	global_store_dword v[196:197], v139, off offset:64
	global_store_dword v[196:197], v140, off offset:128
	global_store_dword v[196:197], v141, off offset:192
	v_lshl_add_u64 v[196:197], v[196:197], 0, s[98:99]
	s_waitcnt vmcnt(60)
; DI void phase_gemm_out(const Params& p, int bid, int nb, char* smem) {
;     ...
; #pragma unroll
;     for (int mt = 0; mt < 4; mt++)
; #pragma unroll
;       for (int r4 = 0; r4 < 4; r4++) {
;         const int row = tm * 128 + wm * 64 + mt * 16 + g * 4 + r4;
; #pragma unroll
;         for (int nt = 0; nt < 4; nt++) {
;           const size_t idx = (size_t)row * 1024 + tn * 128 + wn * 64 + nt * 16 + l15;
;           p.out[idx] = p.x[idx] + acc[mt][nt][r4];
	v_add_f32_e32 v142, v73, v142
	v_add_f32_e32 v143, v77, v143
	v_add_f32_e32 v144, v89, v144
	v_add_f32_e32 v145, v105, v145
	global_store_dword v[196:197], v142, off
	global_store_dword v[196:197], v143, off offset:64
	global_store_dword v[196:197], v144, off offset:128
	global_store_dword v[196:197], v145, off offset:192
	s_mov_b64 s[98:99], 0xd000
	v_lshl_add_u64 v[196:197], v[196:197], 0, s[98:99]
	s_mov_b64 s[98:99], 0x1000
	s_waitcnt vmcnt(60)
	v_add_f32_e32 v146, v106, v146
	v_add_f32_e32 v147, v110, v147
	v_add_f32_e32 v148, v114, v148
	v_add_f32_e32 v149, v62, v149
	global_store_dword v[196:197], v146, off
	global_store_dword v[196:197], v147, off offset:64
	global_store_dword v[196:197], v148, off offset:128
	global_store_dword v[196:197], v149, off offset:192
	v_lshl_add_u64 v[196:197], v[196:197], 0, s[98:99]
	s_waitcnt vmcnt(60)
	v_add_f32_e32 v150, v107, v150
	v_add_f32_e32 v151, v111, v151
	v_add_f32_e32 v152, v115, v152
	v_add_f32_e32 v153, v63, v153
	global_store_dword v[196:197], v150, off
	global_store_dword v[196:197], v151, off offset:64
	global_store_dword v[196:197], v152, off offset:128
	global_store_dword v[196:197], v153, off offset:192
	v_lshl_add_u64 v[196:197], v[196:197], 0, s[98:99]
	s_waitcnt vmcnt(60)
	v_add_f32_e32 v154, v108, v154
	v_add_f32_e32 v155, v112, v155
	v_add_f32_e32 v156, v116, v156
	v_add_f32_e32 v157, v64, v157
	global_store_dword v[196:197], v154, off
	global_store_dword v[196:197], v155, off offset:64
	global_store_dword v[196:197], v156, off offset:128
	global_store_dword v[196:197], v157, off offset:192
	v_lshl_add_u64 v[196:197], v[196:197], 0, s[98:99]
	s_waitcnt vmcnt(60)
	v_add_f32_e32 v158, v109, v158
	v_add_f32_e32 v159, v113, v159
	v_add_f32_e32 v160, v117, v160
	v_add_f32_e32 v161, v65, v161
	global_store_dword v[196:197], v158, off
	global_store_dword v[196:197], v159, off offset:64
	global_store_dword v[196:197], v160, off offset:128
	global_store_dword v[196:197], v161, off offset:192
	s_mov_b64 s[98:99], 0xd000
	v_lshl_add_u64 v[196:197], v[196:197], 0, s[98:99]
	s_mov_b64 s[98:99], 0x1000
	s_waitcnt vmcnt(60)
	v_add_f32_e32 v162, v30, v162
	v_add_f32_e32 v163, v26, v163
	v_add_f32_e32 v164, v22, v164
	v_add_f32_e32 v165, v18, v165
	global_store_dword v[196:197], v162, off
	global_store_dword v[196:197], v163, off offset:64
	global_store_dword v[196:197], v164, off offset:128
	global_store_dword v[196:197], v165, off offset:192
	v_lshl_add_u64 v[196:197], v[196:197], 0, s[98:99]
	s_waitcnt vmcnt(60)
	v_add_f32_e32 v166, v31, v166
	v_add_f32_e32 v167, v27, v167
	v_add_f32_e32 v168, v23, v168
	v_add_f32_e32 v169, v19, v169
	global_store_dword v[196:197], v166, off
	global_store_dword v[196:197], v167, off offset:64
	global_store_dword v[196:197], v168, off offset:128
	global_store_dword v[196:197], v169, off offset:192
	v_lshl_add_u64 v[196:197], v[196:197], 0, s[98:99]
	s_waitcnt vmcnt(60)
	v_add_f32_e32 v170, v32, v170
	v_add_f32_e32 v171, v28, v171
	v_add_f32_e32 v172, v24, v172
	v_add_f32_e32 v173, v20, v173
	global_store_dword v[196:197], v170, off
	global_store_dword v[196:197], v171, off offset:64
	global_store_dword v[196:197], v172, off offset:128
	global_store_dword v[196:197], v173, off offset:192
	v_lshl_add_u64 v[196:197], v[196:197], 0, s[98:99]
	s_waitcnt vmcnt(60)
	v_add_f32_e32 v174, v33, v174
	v_add_f32_e32 v175, v29, v175
	v_add_f32_e32 v176, v25, v176
	v_add_f32_e32 v177, v21, v177
	global_store_dword v[196:197], v174, off
	global_store_dword v[196:197], v175, off offset:64
	global_store_dword v[196:197], v176, off offset:128
	global_store_dword v[196:197], v177, off offset:192
	s_mov_b64 s[98:99], 0xd000
	v_lshl_add_u64 v[196:197], v[196:197], 0, s[98:99]
	s_mov_b64 s[98:99], 0x1000
	s_waitcnt vmcnt(60)
	v_add_f32_e32 v178, v14, v178
	v_add_f32_e32 v179, v10, v179
	v_add_f32_e32 v180, v6, v180
	v_add_f32_e32 v181, v2, v181
	global_store_dword v[196:197], v178, off
	global_store_dword v[196:197], v179, off offset:64
	global_store_dword v[196:197], v180, off offset:128
	global_store_dword v[196:197], v181, off offset:192
	v_lshl_add_u64 v[196:197], v[196:197], 0, s[98:99]
	s_waitcnt vmcnt(60)
	v_add_f32_e32 v182, v15, v182
	v_add_f32_e32 v183, v11, v183
	v_add_f32_e32 v184, v7, v184
	v_add_f32_e32 v185, v3, v185
	global_store_dword v[196:197], v182, off
	global_store_dword v[196:197], v183, off offset:64
	global_store_dword v[196:197], v184, off offset:128
	global_store_dword v[196:197], v185, off offset:192
	v_lshl_add_u64 v[196:197], v[196:197], 0, s[98:99]
	s_waitcnt vmcnt(60)
	v_add_f32_e32 v186, v16, v186
	v_add_f32_e32 v187, v12, v187
	v_add_f32_e32 v188, v8, v188
	v_add_f32_e32 v189, v4, v189
	global_store_dword v[196:197], v186, off
	global_store_dword v[196:197], v187, off offset:64
	global_store_dword v[196:197], v188, off offset:128
	global_store_dword v[196:197], v189, off offset:192
	v_lshl_add_u64 v[196:197], v[196:197], 0, s[98:99]
	s_waitcnt vmcnt(60)
	v_add_f32_e32 v190, v17, v190
	v_add_f32_e32 v191, v13, v191
	v_add_f32_e32 v192, v9, v192
	v_add_f32_e32 v193, v5, v193
	global_store_dword v[196:197], v190, off
	global_store_dword v[196:197], v191, off offset:64
	global_store_dword v[196:197], v192, off offset:128
	global_store_dword v[196:197], v193, off offset:192
	s_cmpk_lt_i32 s8, 0x80
	s_cbranch_scc1 .LBB0_1043

; DI unsigned xb_xcc_id() { return (unsigned)__builtin_amdgcn_s_getreg((3 << 11) | 20) & 0xFu; }
; DI void phase_peer_u(const Params& p, char* smem) {
;   const int tid = threadIdx.x, lane = tid & 63, wave = tid >> 6;
;   const int pg = lane >> 3, cq = lane & 7;
;   const unsigned xcc = xb_xcc_id() & 7u;
;   volatile int* qslot = (volatile int*)smem;
;   unsigned* cnt = p.bar + 4096;
;   const bool b0 = (lane & 1) != 0, b1 = (lane & 2) != 0, b2 = (lane & 4) != 0;
;   const int ibase = (b0 ? 8 : 0) + (b1 ? 4 : 0) + (b2 ? 2 : 0);
; DI void phase_peer_v(const Params& p, char* smem) {
;   const int tid = threadIdx.x, lane = tid & 63, wave = tid >> 6;
;   const int pg = lane >> 3, cq = lane & 7;
;   const unsigned xcc = xb_xcc_id() & 7u;
;   volatile int* qslot = (volatile int*)smem;
;   unsigned* cnt = p.bar + 4096 + 16;
;   for (int pi = 0; pi < 8; pi++) {
;     const int slice = (int)((xcc + (unsigned)pi) & 7u);
;     const unsigned char* vbase = p.vb8 + (size_t)slice * 16384 * 128 + cq * 16;
.LBB0_1316:
	s_cmp_gt_i32 s48, 9
	s_cselect_b64 s[0:1], -1, 0
	s_cmp_lt_i32 s49, 10
	s_cselect_b64 s[2:3], -1, 0
	s_or_b64 s[0:1], s[0:1], s[2:3]
	s_and_b64 vcc, exec, s[0:1]
	v_bfe_u32 v180, v0, 3, 3
	v_and_b32_e32 v146, 63, v0
	v_mbcnt_lo_u32_b32 v181, -1, 0
	s_cbranch_vccnz .LBB0_1412
	v_and_b32_e32 v1, 0x3ff, v0
	v_and_b32_e32 v2, 63, v1
	v_lshlrev_b32_e32 v3, 4, v2
	v_and_b32_e32 v3, 0x70, v3
	v_lshrrev_b32_e32 v4, 3, v2
	v_lshrrev_b32_e32 v5, 6, v1
	v_readlane_b32 s2, v253, 10
	v_readlane_b32 s3, v253, 11
	v_readlane_b32 s33, v253, 8
	s_sub_u32 s2, s2, 0x1c8
	s_subb_u32 s3, s3, 0
	s_load_dwordx2 s[4:5], s[2:3], 0x88
	s_load_dwordx2 s[6:7], s[2:3], 0x190
	s_load_dwordx2 s[8:9], s[2:3], 0x188
	s_load_dwordx2 s[10:11], s[2:3], 0x1a8
	s_load_dwordx2 s[12:13], s[2:3], 0x150
	s_load_dwordx2 s[14:15], s[2:3], 0x1b8
	s_load_dwordx2 s[58:59], s[2:3], 0x130
	s_getreg_b32 s16, hwreg(HW_REG_XCC_ID, 0, 4)
	s_and_b32 s16, s16, 7
	v_mul_u32_u24_e32 v228, 0x3000, v5
	v_add_u32_e32 v228, 0x400, v228
	v_and_b32_e32 v6, 7, v2
	v_lshlrev_b32_e32 v6, 4, v6
	v_add_u32_e32 v6, v6, v4
	v_lshl_add_u32 v229, v6, 2, v228
	v_lshl_add_u32 v241, v2, 3, v228
	v_and_b32_e32 v6, 1, v2
	v_lshlrev_b32_e32 v6, 3, v6
	v_and_b32_e32 v7, 2, v2
	v_lshl_or_b32 v6, v7, 1, v6
	v_and_b32_e32 v7, 4, v2
	v_lshrrev_b32_e32 v7, 1, v7
	v_or_b32_e32 v6, v6, v7
	v_lshl_add_u32 v7, v4, 4, v6
	v_lshl_add_u32 v238, v7, 2, v228
	v_and_b32_e32 v7, 7, v6
	v_lshl_add_u32 v7, v7, 3, v4
	v_lshrrev_b32_e32 v6, 3, v6
	v_lshl_add_u32 v7, v6, 6, v7
	v_lshlrev_b32_e32 v239, 2, v7
	v_lshl_add_u32 v228, v4, 6, v228
	v_xor_b32_e32 v230, 16, v2
	v_lshlrev_b32_e32 v230, 2, v230
	v_lshrrev_b32_e32 v6, 2, v2
	v_and_b32_e32 v6, 14, v6
	v_add_u32_e32 v6, v6, v3
	v_lshlrev_b32_e32 v231, 2, v6
	v_lshlrev_b32_e32 v237, 2, v2
	v_lshlrev_b32_e32 v240, 1, v3
	v_and_b32_e32 v6, 16, v2
	v_cmp_eq_u32_e64 s[52:53], 0, v6
	v_and_b32_e32 v6, 8, v2
	v_cmp_eq_u32_e64 s[54:55], 0, v6
	v_and_b32_e32 v6, 1, v2
	v_cmp_eq_u32_e64 s[60:61], 0, v6
	v_and_b32_e32 v6, 2, v2
	v_cmp_eq_u32_e64 s[62:63], 0, v6
	v_and_b32_e32 v6, 4, v2
	v_cmp_eq_u32_e64 s[64:65], 0, v6
	v_readfirstlane_b32 s34, v5
	s_lshl_b32 s34, s34, 3
	s_mov_b32 s18, s100
	s_cmpk_lt_u32 s100, 0x200
	s_cbranch_scc0 .Lpeer_done
	s_waitcnt lgkmcnt(0)

; DI void phase_peer_v(const Params& p, char* smem) {
;     ...
;         float2* op = (float2*)(p.out + (size_t)t * 1024 + slice * 128 + col);
;         float2 ov = *op;
; #pragma unroll
;         for (int i = 0; i < 16; i++) {
;           const int e = __shfl(i < 8 ? e1a : e1b, 8 * (i & 7) + pg);
;           R1[i] = *(const u32x4*)(vbase + (size_t)e * 128);
;         }
;         __builtin_amdgcn_sched_barrier(0);
;         f32x2 acc[8];
; #pragma unroll
;         for (int j = 0; j < 8; j++) acc[j] = (f32x2){0.f, 0.f};
; #pragma unroll
;         for (int i = 0; i < 16; i++) {
;           const float a = __shfl(i < 8 ? a0a : a0b, 8 * (i & 7) + pg);
;           f32x2 f[8];
;           unpack_fp8x16(R0[i], f);
;           const f32x2 a2 = {a, a};
; #pragma unroll
;           for (int j = 0; j < 8; j++) acc[j] += a2 * f[j];
;         }
.Lpeer_vstep:
	s_and_b32 s24, s17, 7
	s_lshr_b32 s25, s17, 3
	s_add_u32 s25, s25, s16
	s_and_b32 s25, s25, 7
	s_add_u32 s30, s19, s24
	s_lshl_b32 s31, s30, 12
	s_lshl_b32 s32, s25, 9
	s_add_u32 s31, s31, s32
	s_add_u32 s22, s4, s31
	s_addc_u32 s23, s5, 0
	global_load_dwordx2 v[138:139], v231, s[22:23] nt
	s_add_u32 s38, s17, 1
	s_and_b32 s38, s38, 63
	s_lshr_b32 s24, s38, 3
	s_add_u32 s24, s24, s16
	s_and_b32 s24, s24, 7
	s_lshl_b32 s24, s24, 21
	s_add_u32 s20, s6, s24
	s_addc_u32 s21, s7, 0
	s_waitcnt vmcnt(17)
	v_cvt_pk_f32_fp8_e32 v[72:73], v8
	v_cvt_pk_f32_fp8_sdwa v[74:75], v8 src0_sel:WORD_1
	v_cvt_pk_f32_fp8_e32 v[76:77], v9
	v_cvt_pk_f32_fp8_sdwa v[78:79], v9 src0_sel:WORD_1
	v_cvt_pk_f32_fp8_e32 v[80:81], v10
	v_cvt_pk_f32_fp8_sdwa v[82:83], v10 src0_sel:WORD_1
	v_cvt_pk_f32_fp8_e32 v[84:85], v11
	v_cvt_pk_f32_fp8_sdwa v[86:87], v11 src0_sel:WORD_1
	v_pk_mul_f32 v[88:89], v[104:105], v[72:73] op_sel_hi:[0,1]
	v_pk_mul_f32 v[90:91], v[104:105], v[74:75] op_sel_hi:[0,1]
	v_pk_mul_f32 v[92:93], v[104:105], v[76:77] op_sel_hi:[0,1]
	v_pk_mul_f32 v[94:95], v[104:105], v[78:79] op_sel_hi:[0,1]
	v_pk_mul_f32 v[96:97], v[104:105], v[80:81] op_sel_hi:[0,1]
	v_pk_mul_f32 v[98:99], v[104:105], v[82:83] op_sel_hi:[0,1]
	v_pk_mul_f32 v[100:101], v[104:105], v[84:85] op_sel_hi:[0,1]
	v_pk_mul_f32 v[102:103], v[104:105], v[86:87] op_sel_hi:[0,1]
	v_or_b32_e32 v136, v120, v3
	global_load_dwordx4 v[8:11], v136, s[20:21]
	s_waitcnt vmcnt(17)
	v_cvt_pk_f32_fp8_e32 v[72:73], v12
	v_cvt_pk_f32_fp8_sdwa v[74:75], v12 src0_sel:WORD_1
	v_cvt_pk_f32_fp8_e32 v[76:77], v13
	v_cvt_pk_f32_fp8_sdwa v[78:79], v13 src0_sel:WORD_1
	v_cvt_pk_f32_fp8_e32 v[80:81], v14
	v_cvt_pk_f32_fp8_sdwa v[82:83], v14 src0_sel:WORD_1
	v_cvt_pk_f32_fp8_e32 v[84:85], v15
	v_cvt_pk_f32_fp8_sdwa v[86:87], v15 src0_sel:WORD_1
	v_pk_fma_f32 v[88:89], v[104:105], v[72:73], v[88:89] op_sel:[1,0,0] op_sel_hi:[1,1,1]
	v_pk_fma_f32 v[90:91], v[104:105], v[74:75], v[90:91] op_sel:[1,0,0] op_sel_hi:[1,1,1]
	v_pk_fma_f32 v[92:93], v[104:105], v[76:77], v[92:93] op_sel:[1,0,0] op_sel_hi:[1,1,1]
	v_pk_fma_f32 v[94:95], v[104:105], v[78:79], v[94:95] op_sel:[1,0,0] op_sel_hi:[1,1,1]
	v_pk_fma_f32 v[96:97], v[104:105], v[80:81], v[96:97] op_sel:[1,0,0] op_sel_hi:[1,1,1]
	v_pk_fma_f32 v[98:99], v[104:105], v[82:83], v[98:99] op_sel:[1,0,0] op_sel_hi:[1,1,1]
	v_pk_fma_f32 v[100:101], v[104:105], v[84:85], v[100:101] op_sel:[1,0,0] op_sel_hi:[1,1,1]
	v_pk_fma_f32 v[102:103], v[104:105], v[86:87], v[102:103] op_sel:[1,0,0] op_sel_hi:[1,1,1]
	v_or_b32_e32 v137, v121, v3
	global_load_dwordx4 v[12:15], v137, s[20:21]
	s_waitcnt vmcnt(17)
	v_cvt_pk_f32_fp8_e32 v[72:73], v16
	v_cvt_pk_f32_fp8_sdwa v[74:75], v16 src0_sel:WORD_1
	v_cvt_pk_f32_fp8_e32 v[76:77], v17
	v_cvt_pk_f32_fp8_sdwa v[78:79], v17 src0_sel:WORD_1
	v_cvt_pk_f32_fp8_e32 v[80:81], v18
	v_cvt_pk_f32_fp8_sdwa v[82:83], v18 src0_sel:WORD_1
	v_cvt_pk_f32_fp8_e32 v[84:85], v19
	v_cvt_pk_f32_fp8_sdwa v[86:87], v19 src0_sel:WORD_1
	v_pk_fma_f32 v[88:89], v[106:107], v[72:73], v[88:89] op_sel_hi:[0,1,1]
	v_pk_fma_f32 v[90:91], v[106:107], v[74:75], v[90:91] op_sel_hi:[0,1,1]
	v_pk_fma_f32 v[92:93], v[106:107], v[76:77], v[92:93] op_sel_hi:[0,1,1]
	v_pk_fma_f32 v[94:95], v[106:107], v[78:79], v[94:95] op_sel_hi:[0,1,1]
	v_pk_fma_f32 v[96:97], v[106:107], v[80:81], v[96:97] op_sel_hi:[0,1,1]
	v_pk_fma_f32 v[98:99], v[106:107], v[82:83], v[98:99] op_sel_hi:[0,1,1]
	v_pk_fma_f32 v[100:101], v[106:107], v[84:85], v[100:101] op_sel_hi:[0,1,1]
	v_pk_fma_f32 v[102:103], v[106:107], v[86:87], v[102:103] op_sel_hi:[0,1,1]
	v_or_b32_e32 v235, v122, v3
	global_load_dwordx4 v[16:19], v235, s[20:21]
	s_waitcnt vmcnt(17)
	v_cvt_pk_f32_fp8_e32 v[72:73], v20
	v_cvt_pk_f32_fp8_sdwa v[74:75], v20 src0_sel:WORD_1
	v_cvt_pk_f32_fp8_e32 v[76:77], v21
	v_cvt_pk_f32_fp8_sdwa v[78:79], v21 src0_sel:WORD_1
	v_cvt_pk_f32_fp8_e32 v[80:81], v22
	v_cvt_pk_f32_fp8_sdwa v[82:83], v22 src0_sel:WORD_1
	v_cvt_pk_f32_fp8_e32 v[84:85], v23
	v_cvt_pk_f32_fp8_sdwa v[86:87], v23 src0_sel:WORD_1
	v_pk_fma_f32 v[88:89], v[106:107], v[72:73], v[88:89] op_sel:[1,0,0] op_sel_hi:[1,1,1]
	v_pk_fma_f32 v[90:91], v[106:107], v[74:75], v[90:91] op_sel:[1,0,0] op_sel_hi:[1,1,1]
	v_pk_fma_f32 v[92:93], v[106:107], v[76:77], v[92:93] op_sel:[1,0,0] op_sel_hi:[1,1,1]
	v_pk_fma_f32 v[94:95], v[106:107], v[78:79], v[94:95] op_sel:[1,0,0] op_sel_hi:[1,1,1]
	v_pk_fma_f32 v[96:97], v[106:107], v[80:81], v[96:97] op_sel:[1,0,0] op_sel_hi:[1,1,1]
	v_pk_fma_f32 v[98:99], v[106:107], v[82:83], v[98:99] op_sel:[1,0,0] op_sel_hi:[1,1,1]
	v_pk_fma_f32 v[100:101], v[106:107], v[84:85], v[100:101] op_sel:[1,0,0] op_sel_hi:[1,1,1]
	v_pk_fma_f32 v[102:103], v[106:107], v[86:87], v[102:103] op_sel:[1,0,0] op_sel_hi:[1,1,1]
	v_or_b32_e32 v236, v123, v3
	global_load_dwordx4 v[20:23], v236, s[20:21]
	s_waitcnt vmcnt(17)
	v_cvt_pk_f32_fp8_e32 v[72:73], v24
	v_cvt_pk_f32_fp8_sdwa v[74:75], v24 src0_sel:WORD_1
	v_cvt_pk_f32_fp8_e32 v[76:77], v25
	v_cvt_pk_f32_fp8_sdwa v[78:79], v25 src0_sel:WORD_1
	v_cvt_pk_f32_fp8_e32 v[80:81], v26
	v_cvt_pk_f32_fp8_sdwa v[82:83], v26 src0_sel:WORD_1
	v_cvt_pk_f32_fp8_e32 v[84:85], v27
	v_cvt_pk_f32_fp8_sdwa v[86:87], v27 src0_sel:WORD_1
	v_pk_fma_f32 v[88:89], v[108:109], v[72:73], v[88:89] op_sel_hi:[0,1,1]
	v_pk_fma_f32 v[90:91], v[108:109], v[74:75], v[90:91] op_sel_hi:[0,1,1]
	v_pk_fma_f32 v[92:93], v[108:109], v[76:77], v[92:93] op_sel_hi:[0,1,1]
	v_pk_fma_f32 v[94:95], v[108:109], v[78:79], v[94:95] op_sel_hi:[0,1,1]
	v_pk_fma_f32 v[96:97], v[108:109], v[80:81], v[96:97] op_sel_hi:[0,1,1]
	v_pk_fma_f32 v[98:99], v[108:109], v[82:83], v[98:99] op_sel_hi:[0,1,1]
	v_pk_fma_f32 v[100:101], v[108:109], v[84:85], v[100:101] op_sel_hi:[0,1,1]
	v_pk_fma_f32 v[102:103], v[108:109], v[86:87], v[102:103] op_sel_hi:[0,1,1]
	v_or_b32_e32 v136, v124, v3
	global_load_dwordx4 v[24:27], v136, s[20:21]
	s_waitcnt vmcnt(17)
; DI void phase_peer_v(const Params& p, char* smem) {
;     ...
;         for (int i = 0; i < 16; i++) {
;           const float a = __shfl(i < 8 ? a0a : a0b, 8 * (i & 7) + pg);
;           f32x2 f[8];
;           unpack_fp8x16(R0[i], f);
;           const f32x2 a2 = {a, a};
; #pragma unroll
;           for (int j = 0; j < 8; j++) acc[j] += a2 * f[j];
;         }
	v_cvt_pk_f32_fp8_e32 v[72:73], v28
	v_cvt_pk_f32_fp8_sdwa v[74:75], v28 src0_sel:WORD_1
	v_cvt_pk_f32_fp8_e32 v[76:77], v29
	v_cvt_pk_f32_fp8_sdwa v[78:79], v29 src0_sel:WORD_1
	v_cvt_pk_f32_fp8_e32 v[80:81], v30
	v_cvt_pk_f32_fp8_sdwa v[82:83], v30 src0_sel:WORD_1
	v_cvt_pk_f32_fp8_e32 v[84:85], v31
	v_cvt_pk_f32_fp8_sdwa v[86:87], v31 src0_sel:WORD_1
	v_pk_fma_f32 v[88:89], v[108:109], v[72:73], v[88:89] op_sel:[1,0,0] op_sel_hi:[1,1,1]
	v_pk_fma_f32 v[90:91], v[108:109], v[74:75], v[90:91] op_sel:[1,0,0] op_sel_hi:[1,1,1]
	v_pk_fma_f32 v[92:93], v[108:109], v[76:77], v[92:93] op_sel:[1,0,0] op_sel_hi:[1,1,1]
	v_pk_fma_f32 v[94:95], v[108:109], v[78:79], v[94:95] op_sel:[1,0,0] op_sel_hi:[1,1,1]
	v_pk_fma_f32 v[96:97], v[108:109], v[80:81], v[96:97] op_sel:[1,0,0] op_sel_hi:[1,1,1]
	v_pk_fma_f32 v[98:99], v[108:109], v[82:83], v[98:99] op_sel:[1,0,0] op_sel_hi:[1,1,1]
	v_pk_fma_f32 v[100:101], v[108:109], v[84:85], v[100:101] op_sel:[1,0,0] op_sel_hi:[1,1,1]
	v_pk_fma_f32 v[102:103], v[108:109], v[86:87], v[102:103] op_sel:[1,0,0] op_sel_hi:[1,1,1]
	v_or_b32_e32 v137, v125, v3
	global_load_dwordx4 v[28:31], v137, s[20:21]
	s_waitcnt vmcnt(17)
	v_cvt_pk_f32_fp8_e32 v[72:73], v32
	v_cvt_pk_f32_fp8_sdwa v[74:75], v32 src0_sel:WORD_1
	v_cvt_pk_f32_fp8_e32 v[76:77], v33
	v_cvt_pk_f32_fp8_sdwa v[78:79], v33 src0_sel:WORD_1
	v_cvt_pk_f32_fp8_e32 v[80:81], v34
	v_cvt_pk_f32_fp8_sdwa v[82:83], v34 src0_sel:WORD_1
	v_cvt_pk_f32_fp8_e32 v[84:85], v35
	v_cvt_pk_f32_fp8_sdwa v[86:87], v35 src0_sel:WORD_1
	v_pk_fma_f32 v[88:89], v[110:111], v[72:73], v[88:89] op_sel_hi:[0,1,1]
	v_pk_fma_f32 v[90:91], v[110:111], v[74:75], v[90:91] op_sel_hi:[0,1,1]
	v_pk_fma_f32 v[92:93], v[110:111], v[76:77], v[92:93] op_sel_hi:[0,1,1]
	v_pk_fma_f32 v[94:95], v[110:111], v[78:79], v[94:95] op_sel_hi:[0,1,1]
	v_pk_fma_f32 v[96:97], v[110:111], v[80:81], v[96:97] op_sel_hi:[0,1,1]
	v_pk_fma_f32 v[98:99], v[110:111], v[82:83], v[98:99] op_sel_hi:[0,1,1]
	v_pk_fma_f32 v[100:101], v[110:111], v[84:85], v[100:101] op_sel_hi:[0,1,1]
	v_pk_fma_f32 v[102:103], v[110:111], v[86:87], v[102:103] op_sel_hi:[0,1,1]
	v_or_b32_e32 v235, v126, v3
	global_load_dwordx4 v[32:35], v235, s[20:21]
	s_waitcnt vmcnt(17)
	v_cvt_pk_f32_fp8_e32 v[72:73], v36
	v_cvt_pk_f32_fp8_sdwa v[74:75], v36 src0_sel:WORD_1
	v_cvt_pk_f32_fp8_e32 v[76:77], v37
	v_cvt_pk_f32_fp8_sdwa v[78:79], v37 src0_sel:WORD_1
	v_cvt_pk_f32_fp8_e32 v[80:81], v38
	v_cvt_pk_f32_fp8_sdwa v[82:83], v38 src0_sel:WORD_1
	v_cvt_pk_f32_fp8_e32 v[84:85], v39
	v_cvt_pk_f32_fp8_sdwa v[86:87], v39 src0_sel:WORD_1
	v_pk_fma_f32 v[88:89], v[110:111], v[72:73], v[88:89] op_sel:[1,0,0] op_sel_hi:[1,1,1]
	v_pk_fma_f32 v[90:91], v[110:111], v[74:75], v[90:91] op_sel:[1,0,0] op_sel_hi:[1,1,1]
	v_pk_fma_f32 v[92:93], v[110:111], v[76:77], v[92:93] op_sel:[1,0,0] op_sel_hi:[1,1,1]
	v_pk_fma_f32 v[94:95], v[110:111], v[78:79], v[94:95] op_sel:[1,0,0] op_sel_hi:[1,1,1]
	v_pk_fma_f32 v[96:97], v[110:111], v[80:81], v[96:97] op_sel:[1,0,0] op_sel_hi:[1,1,1]
	v_pk_fma_f32 v[98:99], v[110:111], v[82:83], v[98:99] op_sel:[1,0,0] op_sel_hi:[1,1,1]
	v_pk_fma_f32 v[100:101], v[110:111], v[84:85], v[100:101] op_sel:[1,0,0] op_sel_hi:[1,1,1]
	v_pk_fma_f32 v[102:103], v[110:111], v[86:87], v[102:103] op_sel:[1,0,0] op_sel_hi:[1,1,1]
	v_or_b32_e32 v236, v127, v3
	global_load_dwordx4 v[36:39], v236, s[20:21]
	s_waitcnt vmcnt(17)
	v_cvt_pk_f32_fp8_e32 v[72:73], v40
	v_cvt_pk_f32_fp8_sdwa v[74:75], v40 src0_sel:WORD_1
	v_cvt_pk_f32_fp8_e32 v[76:77], v41
	v_cvt_pk_f32_fp8_sdwa v[78:79], v41 src0_sel:WORD_1
	v_cvt_pk_f32_fp8_e32 v[80:81], v42
	v_cvt_pk_f32_fp8_sdwa v[82:83], v42 src0_sel:WORD_1
	v_cvt_pk_f32_fp8_e32 v[84:85], v43
	v_cvt_pk_f32_fp8_sdwa v[86:87], v43 src0_sel:WORD_1
	v_pk_fma_f32 v[88:89], v[112:113], v[72:73], v[88:89] op_sel_hi:[0,1,1]
	v_pk_fma_f32 v[90:91], v[112:113], v[74:75], v[90:91] op_sel_hi:[0,1,1]
	v_pk_fma_f32 v[92:93], v[112:113], v[76:77], v[92:93] op_sel_hi:[0,1,1]
	v_pk_fma_f32 v[94:95], v[112:113], v[78:79], v[94:95] op_sel_hi:[0,1,1]
	v_pk_fma_f32 v[96:97], v[112:113], v[80:81], v[96:97] op_sel_hi:[0,1,1]
	v_pk_fma_f32 v[98:99], v[112:113], v[82:83], v[98:99] op_sel_hi:[0,1,1]
	v_pk_fma_f32 v[100:101], v[112:113], v[84:85], v[100:101] op_sel_hi:[0,1,1]
	v_pk_fma_f32 v[102:103], v[112:113], v[86:87], v[102:103] op_sel_hi:[0,1,1]
	v_or_b32_e32 v136, v128, v3
	global_load_dwordx4 v[40:43], v136, s[20:21]
	s_waitcnt vmcnt(17)
	v_cvt_pk_f32_fp8_e32 v[72:73], v44
	v_cvt_pk_f32_fp8_sdwa v[74:75], v44 src0_sel:WORD_1
	v_cvt_pk_f32_fp8_e32 v[76:77], v45
	v_cvt_pk_f32_fp8_sdwa v[78:79], v45 src0_sel:WORD_1
	v_cvt_pk_f32_fp8_e32 v[80:81], v46
	v_cvt_pk_f32_fp8_sdwa v[82:83], v46 src0_sel:WORD_1
	v_cvt_pk_f32_fp8_e32 v[84:85], v47
	v_cvt_pk_f32_fp8_sdwa v[86:87], v47 src0_sel:WORD_1
	v_pk_fma_f32 v[88:89], v[112:113], v[72:73], v[88:89] op_sel:[1,0,0] op_sel_hi:[1,1,1]
	v_pk_fma_f32 v[90:91], v[112:113], v[74:75], v[90:91] op_sel:[1,0,0] op_sel_hi:[1,1,1]
	v_pk_fma_f32 v[92:93], v[112:113], v[76:77], v[92:93] op_sel:[1,0,0] op_sel_hi:[1,1,1]
	v_pk_fma_f32 v[94:95], v[112:113], v[78:79], v[94:95] op_sel:[1,0,0] op_sel_hi:[1,1,1]
	v_pk_fma_f32 v[96:97], v[112:113], v[80:81], v[96:97] op_sel:[1,0,0] op_sel_hi:[1,1,1]
	v_pk_fma_f32 v[98:99], v[112:113], v[82:83], v[98:99] op_sel:[1,0,0] op_sel_hi:[1,1,1]
	v_pk_fma_f32 v[100:101], v[112:113], v[84:85], v[100:101] op_sel:[1,0,0] op_sel_hi:[1,1,1]
	v_pk_fma_f32 v[102:103], v[112:113], v[86:87], v[102:103] op_sel:[1,0,0] op_sel_hi:[1,1,1]
	v_or_b32_e32 v137, v129, v3
	global_load_dwordx4 v[44:47], v137, s[20:21]
	s_waitcnt vmcnt(17)
; DI void phase_peer_v(const Params& p, char* smem) {
;     ...
;         for (int i = 0; i < 16; i++) {
;           const float a = __shfl(i < 8 ? a0a : a0b, 8 * (i & 7) + pg);
;           f32x2 f[8];
;           unpack_fp8x16(R0[i], f);
;           const f32x2 a2 = {a, a};
; #pragma unroll
;           for (int j = 0; j < 8; j++) acc[j] += a2 * f[j];
;         }
	v_cvt_pk_f32_fp8_e32 v[72:73], v48
	v_cvt_pk_f32_fp8_sdwa v[74:75], v48 src0_sel:WORD_1
	v_cvt_pk_f32_fp8_e32 v[76:77], v49
	v_cvt_pk_f32_fp8_sdwa v[78:79], v49 src0_sel:WORD_1
	v_cvt_pk_f32_fp8_e32 v[80:81], v50
	v_cvt_pk_f32_fp8_sdwa v[82:83], v50 src0_sel:WORD_1
	v_cvt_pk_f32_fp8_e32 v[84:85], v51
	v_cvt_pk_f32_fp8_sdwa v[86:87], v51 src0_sel:WORD_1
	v_pk_fma_f32 v[88:89], v[114:115], v[72:73], v[88:89] op_sel_hi:[0,1,1]
	v_pk_fma_f32 v[90:91], v[114:115], v[74:75], v[90:91] op_sel_hi:[0,1,1]
	v_pk_fma_f32 v[92:93], v[114:115], v[76:77], v[92:93] op_sel_hi:[0,1,1]
	v_pk_fma_f32 v[94:95], v[114:115], v[78:79], v[94:95] op_sel_hi:[0,1,1]
	v_pk_fma_f32 v[96:97], v[114:115], v[80:81], v[96:97] op_sel_hi:[0,1,1]
	v_pk_fma_f32 v[98:99], v[114:115], v[82:83], v[98:99] op_sel_hi:[0,1,1]
	v_pk_fma_f32 v[100:101], v[114:115], v[84:85], v[100:101] op_sel_hi:[0,1,1]
	v_pk_fma_f32 v[102:103], v[114:115], v[86:87], v[102:103] op_sel_hi:[0,1,1]
	v_or_b32_e32 v235, v130, v3
	global_load_dwordx4 v[48:51], v235, s[20:21]
	s_waitcnt vmcnt(17)
	v_cvt_pk_f32_fp8_e32 v[72:73], v52
	v_cvt_pk_f32_fp8_sdwa v[74:75], v52 src0_sel:WORD_1
	v_cvt_pk_f32_fp8_e32 v[76:77], v53
	v_cvt_pk_f32_fp8_sdwa v[78:79], v53 src0_sel:WORD_1
	v_cvt_pk_f32_fp8_e32 v[80:81], v54
	v_cvt_pk_f32_fp8_sdwa v[82:83], v54 src0_sel:WORD_1
	v_cvt_pk_f32_fp8_e32 v[84:85], v55
	v_cvt_pk_f32_fp8_sdwa v[86:87], v55 src0_sel:WORD_1
	v_pk_fma_f32 v[88:89], v[114:115], v[72:73], v[88:89] op_sel:[1,0,0] op_sel_hi:[1,1,1]
	v_pk_fma_f32 v[90:91], v[114:115], v[74:75], v[90:91] op_sel:[1,0,0] op_sel_hi:[1,1,1]
	v_pk_fma_f32 v[92:93], v[114:115], v[76:77], v[92:93] op_sel:[1,0,0] op_sel_hi:[1,1,1]
	v_pk_fma_f32 v[94:95], v[114:115], v[78:79], v[94:95] op_sel:[1,0,0] op_sel_hi:[1,1,1]
	v_pk_fma_f32 v[96:97], v[114:115], v[80:81], v[96:97] op_sel:[1,0,0] op_sel_hi:[1,1,1]
	v_pk_fma_f32 v[98:99], v[114:115], v[82:83], v[98:99] op_sel:[1,0,0] op_sel_hi:[1,1,1]
	v_pk_fma_f32 v[100:101], v[114:115], v[84:85], v[100:101] op_sel:[1,0,0] op_sel_hi:[1,1,1]
	v_pk_fma_f32 v[102:103], v[114:115], v[86:87], v[102:103] op_sel:[1,0,0] op_sel_hi:[1,1,1]
	v_or_b32_e32 v236, v131, v3
	global_load_dwordx4 v[52:55], v236, s[20:21]
	s_waitcnt vmcnt(17)
	v_cvt_pk_f32_fp8_e32 v[72:73], v56
	v_cvt_pk_f32_fp8_sdwa v[74:75], v56 src0_sel:WORD_1
	v_cvt_pk_f32_fp8_e32 v[76:77], v57
	v_cvt_pk_f32_fp8_sdwa v[78:79], v57 src0_sel:WORD_1
	v_cvt_pk_f32_fp8_e32 v[80:81], v58
	v_cvt_pk_f32_fp8_sdwa v[82:83], v58 src0_sel:WORD_1
	v_cvt_pk_f32_fp8_e32 v[84:85], v59
	v_cvt_pk_f32_fp8_sdwa v[86:87], v59 src0_sel:WORD_1
	v_pk_fma_f32 v[88:89], v[116:117], v[72:73], v[88:89] op_sel_hi:[0,1,1]
	v_pk_fma_f32 v[90:91], v[116:117], v[74:75], v[90:91] op_sel_hi:[0,1,1]
	v_pk_fma_f32 v[92:93], v[116:117], v[76:77], v[92:93] op_sel_hi:[0,1,1]
	v_pk_fma_f32 v[94:95], v[116:117], v[78:79], v[94:95] op_sel_hi:[0,1,1]
	v_pk_fma_f32 v[96:97], v[116:117], v[80:81], v[96:97] op_sel_hi:[0,1,1]
	v_pk_fma_f32 v[98:99], v[116:117], v[82:83], v[98:99] op_sel_hi:[0,1,1]
	v_pk_fma_f32 v[100:101], v[116:117], v[84:85], v[100:101] op_sel_hi:[0,1,1]
	v_pk_fma_f32 v[102:103], v[116:117], v[86:87], v[102:103] op_sel_hi:[0,1,1]
	v_or_b32_e32 v136, v132, v3
	global_load_dwordx4 v[56:59], v136, s[20:21]
	s_waitcnt vmcnt(17)
	v_cvt_pk_f32_fp8_e32 v[72:73], v60
	v_cvt_pk_f32_fp8_sdwa v[74:75], v60 src0_sel:WORD_1
	v_cvt_pk_f32_fp8_e32 v[76:77], v61
	v_cvt_pk_f32_fp8_sdwa v[78:79], v61 src0_sel:WORD_1
	v_cvt_pk_f32_fp8_e32 v[80:81], v62
	v_cvt_pk_f32_fp8_sdwa v[82:83], v62 src0_sel:WORD_1
	v_cvt_pk_f32_fp8_e32 v[84:85], v63
	v_cvt_pk_f32_fp8_sdwa v[86:87], v63 src0_sel:WORD_1
	v_pk_fma_f32 v[88:89], v[116:117], v[72:73], v[88:89] op_sel:[1,0,0] op_sel_hi:[1,1,1]
	v_pk_fma_f32 v[90:91], v[116:117], v[74:75], v[90:91] op_sel:[1,0,0] op_sel_hi:[1,1,1]
	v_pk_fma_f32 v[92:93], v[116:117], v[76:77], v[92:93] op_sel:[1,0,0] op_sel_hi:[1,1,1]
	v_pk_fma_f32 v[94:95], v[116:117], v[78:79], v[94:95] op_sel:[1,0,0] op_sel_hi:[1,1,1]
	v_pk_fma_f32 v[96:97], v[116:117], v[80:81], v[96:97] op_sel:[1,0,0] op_sel_hi:[1,1,1]
	v_pk_fma_f32 v[98:99], v[116:117], v[82:83], v[98:99] op_sel:[1,0,0] op_sel_hi:[1,1,1]
	v_pk_fma_f32 v[100:101], v[116:117], v[84:85], v[100:101] op_sel:[1,0,0] op_sel_hi:[1,1,1]
	v_pk_fma_f32 v[102:103], v[116:117], v[86:87], v[102:103] op_sel:[1,0,0] op_sel_hi:[1,1,1]
	v_or_b32_e32 v137, v133, v3
	global_load_dwordx4 v[60:63], v137, s[20:21]
	s_waitcnt vmcnt(17)
; DI void phase_peer_v(const Params& p, char* smem) {
;     ...
;         f32x2 r4[4], r2[2], r1;
; #pragma unroll
;         for (int j = 0; j < 4; j++) {
;           const f32x2 send = b5 ? acc[j] : acc[4 + j];
;           const f32x2 keep = b5 ? acc[4 + j] : acc[j];
;           r4[j].x = keep.x + __shfl_xor(send.x, 32); r4[j].y = keep.y + __shfl_xor(send.y, 32);
;         }
; #pragma unroll
;         for (int j = 0; j < 2; j++) {
;           const f32x2 send = b4 ? r4[j] : r4[2 + j];
;           const f32x2 keep = b4 ? r4[2 + j] : r4[j];
;           r2[j].x = keep.x + __shfl_xor(send.x, 16); r2[j].y = keep.y + __shfl_xor(send.y, 16);
;         }
;         {
;           const f32x2 send = b3 ? r2[0] : r2[1];
;           const f32x2 keep = b3 ? r2[1] : r2[0];
;           r1.x = keep.x + __shfl_xor(send.x, 8); r1.y = keep.y + __shfl_xor(send.y, 8);
;         }
;         ov.x += r1.x; ov.y += r1.y; *op = ov;
; #pragma unroll
;         for (int i = 0; i < 16; i++) R0[i] = R1[i];
;         e0a = e1a; e0b = e1b; a0a = a1a; a0b = a1b;
;         e1a = e2a; e1b = e2b;
	v_cvt_pk_f32_fp8_e32 v[72:73], v64
	v_cvt_pk_f32_fp8_sdwa v[74:75], v64 src0_sel:WORD_1
	v_cvt_pk_f32_fp8_e32 v[76:77], v65
	v_cvt_pk_f32_fp8_sdwa v[78:79], v65 src0_sel:WORD_1
	v_cvt_pk_f32_fp8_e32 v[80:81], v66
	v_cvt_pk_f32_fp8_sdwa v[82:83], v66 src0_sel:WORD_1
	v_cvt_pk_f32_fp8_e32 v[84:85], v67
	v_cvt_pk_f32_fp8_sdwa v[86:87], v67 src0_sel:WORD_1
	v_pk_fma_f32 v[88:89], v[118:119], v[72:73], v[88:89] op_sel_hi:[0,1,1]
	v_pk_fma_f32 v[90:91], v[118:119], v[74:75], v[90:91] op_sel_hi:[0,1,1]
	v_pk_fma_f32 v[92:93], v[118:119], v[76:77], v[92:93] op_sel_hi:[0,1,1]
	v_pk_fma_f32 v[94:95], v[118:119], v[78:79], v[94:95] op_sel_hi:[0,1,1]
	v_pk_fma_f32 v[96:97], v[118:119], v[80:81], v[96:97] op_sel_hi:[0,1,1]
	v_pk_fma_f32 v[98:99], v[118:119], v[82:83], v[98:99] op_sel_hi:[0,1,1]
	v_pk_fma_f32 v[100:101], v[118:119], v[84:85], v[100:101] op_sel_hi:[0,1,1]
	v_pk_fma_f32 v[102:103], v[118:119], v[86:87], v[102:103] op_sel_hi:[0,1,1]
	v_or_b32_e32 v235, v134, v3
	global_load_dwordx4 v[64:67], v235, s[20:21]
	s_waitcnt vmcnt(17)
	v_cvt_pk_f32_fp8_e32 v[72:73], v68
	v_cvt_pk_f32_fp8_sdwa v[74:75], v68 src0_sel:WORD_1
	v_cvt_pk_f32_fp8_e32 v[76:77], v69
	v_cvt_pk_f32_fp8_sdwa v[78:79], v69 src0_sel:WORD_1
	v_cvt_pk_f32_fp8_e32 v[80:81], v70
	v_cvt_pk_f32_fp8_sdwa v[82:83], v70 src0_sel:WORD_1
	v_cvt_pk_f32_fp8_e32 v[84:85], v71
	v_cvt_pk_f32_fp8_sdwa v[86:87], v71 src0_sel:WORD_1
	v_pk_fma_f32 v[88:89], v[118:119], v[72:73], v[88:89] op_sel:[1,0,0] op_sel_hi:[1,1,1]
	v_pk_fma_f32 v[90:91], v[118:119], v[74:75], v[90:91] op_sel:[1,0,0] op_sel_hi:[1,1,1]
	v_pk_fma_f32 v[92:93], v[118:119], v[76:77], v[92:93] op_sel:[1,0,0] op_sel_hi:[1,1,1]
	v_pk_fma_f32 v[94:95], v[118:119], v[78:79], v[94:95] op_sel:[1,0,0] op_sel_hi:[1,1,1]
	v_pk_fma_f32 v[96:97], v[118:119], v[80:81], v[96:97] op_sel:[1,0,0] op_sel_hi:[1,1,1]
	v_pk_fma_f32 v[98:99], v[118:119], v[82:83], v[98:99] op_sel:[1,0,0] op_sel_hi:[1,1,1]
	v_pk_fma_f32 v[100:101], v[118:119], v[84:85], v[100:101] op_sel:[1,0,0] op_sel_hi:[1,1,1]
	v_pk_fma_f32 v[102:103], v[118:119], v[86:87], v[102:103] op_sel:[1,0,0] op_sel_hi:[1,1,1]
	v_or_b32_e32 v236, v135, v3
	global_load_dwordx4 v[68:71], v236, s[20:21]
	s_and_b32 s24, s38, 7
	s_lshl_b32 s24, s24, 9
	v_add_u32_e32 v232, s24, v228
	ds_read_b128 v[104:107], v232
	ds_read_b128 v[108:111], v232 offset:16
	ds_read_b128 v[112:115], v232 offset:32
	ds_read_b128 v[116:119], v232 offset:48
	s_add_u32 s24, s17, 2
	s_and_b32 s24, s24, 7
	s_lshl_b32 s24, s24, 9
	v_add_u32_e32 v233, s24, v228
	ds_read_b128 v[120:123], v233 offset:4096
	ds_read_b128 v[124:127], v233 offset:4112
	ds_read_b128 v[128:131], v233 offset:4128
	ds_read_b128 v[132:135], v233 offset:4144
	s_nop 1
	v_permlane32_swap_b32_e32 v88, v96
	v_permlane32_swap_b32_e32 v89, v97
	v_permlane32_swap_b32_e32 v90, v98
	v_permlane32_swap_b32_e32 v91, v99
	v_permlane32_swap_b32_e32 v92, v100
	v_permlane32_swap_b32_e32 v93, v101
	v_permlane32_swap_b32_e32 v94, v102
	v_permlane32_swap_b32_e32 v95, v103
	v_pk_add_f32 v[88:89], v[88:89], v[96:97]
	v_pk_add_f32 v[90:91], v[90:91], v[98:99]
	v_pk_add_f32 v[92:93], v[92:93], v[100:101]
	v_pk_add_f32 v[94:95], v[94:95], v[102:103]
	v_cndmask_b32_e64 v140, v88, v92, s[52:53]
	v_cndmask_b32_e64 v144, v92, v88, s[52:53]
	v_cndmask_b32_e64 v141, v89, v93, s[52:53]
	v_cndmask_b32_e64 v145, v93, v89, s[52:53]
	v_cndmask_b32_e64 v142, v90, v94, s[52:53]
	v_cndmask_b32_e64 v146, v94, v90, s[52:53]
	v_cndmask_b32_e64 v143, v91, v95, s[52:53]
	v_cndmask_b32_e64 v147, v95, v91, s[52:53]
	ds_bpermute_b32 v148, v230, v140
	ds_bpermute_b32 v149, v230, v141
	ds_bpermute_b32 v150, v230, v142
	ds_bpermute_b32 v151, v230, v143
	s_waitcnt lgkmcnt(0)
	v_pk_add_f32 v[144:145], v[144:145], v[148:149]
	v_pk_add_f32 v[146:147], v[146:147], v[150:151]
	s_nop 1
	v_add_f32_dpp v152, v144, v144 row_ror:8 row_mask:0xf bank_mask:0xf
	v_add_f32_dpp v153, v145, v145 row_ror:8 row_mask:0xf bank_mask:0xf
	v_add_f32_dpp v154, v146, v146 row_ror:8 row_mask:0xf bank_mask:0xf
	v_add_f32_dpp v155, v147, v147 row_ror:8 row_mask:0xf bank_mask:0xf
	v_cndmask_b32_e64 v156, v154, v152, s[54:55]
	v_cndmask_b32_e64 v157, v155, v153, s[54:55]
	s_waitcnt vmcnt(16)
	v_pk_add_f32 v[156:157], v[156:157], v[138:139]
	global_store_dwordx2 v231, v[156:157], s[22:23] nt
	s_add_u32 s17, s17, 1
	s_cmp_lt_u32 s17, 64
	s_cbranch_scc1 .Lpeer_vstep
	s_waitcnt vmcnt(0)
	s_add_u32 s18, s18, s33
	s_cmpk_lt_u32 s18, 0x200
	s_cbranch_scc1 .Lpeer_group
.Lpeer_done:
	v_cmp_eq_u32_e64 s[0:1], 0, v1
